# same full stack but with the bit-exact accumulator-stationary MFMA order (accstat) instead of the snake order: outputs identical to baseline numerics
# baseline (speedup 1.0000x reference)
.LBB0_101:
	ds_read_b128 v[154:157], v151
	ds_read_b128 v[158:161], v151 offset:1024
	ds_read_b128 v[162:165], v151 offset:2048
	ds_read_b128 v[166:169], v151 offset:3072
	ds_read_b128 v[170:173], v152
	ds_read_b128 v[174:177], v152 offset:1024
	ds_read_b128 v[188:191], v152 offset:2048
	ds_read_b128 v[192:195], v152 offset:3072
	s_add_u32 s40, s36, s38
	s_addc_u32 s41, s37, s39
	s_add_u32 s44, s40, 0x100
	s_addc_u32 s45, s41, 0
	s_add_u32 s42, s66, s38
	s_addc_u32 s43, s67, s39
	s_add_u32 s40, s40, 0x180
	s_addc_u32 s41, s41, 0
	s_cmpk_eq_i32 s38, 0x1f00
	s_cselect_b32 s41, s65, s41
	s_cselect_b32 s40, s64, s40
	s_cselect_b32 s43, s35, s43
	s_cselect_b32 s42, s34, s42
	s_cselect_b32 s45, s23, s45
	s_cselect_b32 s44, s22, s44
	s_mov_b32 m0, s57
	v_lshl_add_u64 v[178:179], v[146:147], 0, s[38:39]
	ds_read_b128 v[196:199], v153
	ds_read_b128 v[200:203], v153 offset:1024
	ds_read_b128 v[204:207], v153 offset:2048
	ds_read_b128 v[208:211], v153 offset:3072
	ds_read_b128 v[214:217], v153 offset:4096
	ds_read_b128 v[218:221], v153 offset:5120
	ds_read_b128 v[222:225], v153 offset:6144
	ds_read_b128 v[226:229], v153 offset:7168
	global_load_lds_dwordx4 v[178:179], off
	v_lshl_add_u64 v[178:179], v[148:149], 0, s[38:39]
	s_add_i32 m0, s47, 0xe000
	s_nop 0
	global_load_lds_dwordx4 v[178:179], off
	s_waitcnt vmcnt(8)
	s_waitcnt lgkmcnt(0)
	s_barrier
	s_waitcnt lgkmcnt(0)
	v_mfma_f32_16x16x32_bf16 v[126:129], v[154:157], v[196:199], v[126:129]
	v_mfma_f32_16x16x32_bf16 v[126:129], v[158:161], v[200:203], v[126:129]
	v_mfma_f32_16x16x32_bf16 v[122:125], v[162:165], v[196:199], v[122:125]
	v_mfma_f32_16x16x32_bf16 v[122:125], v[166:169], v[200:203], v[122:125]
	v_mfma_f32_16x16x32_bf16 v[118:121], v[154:157], v[204:207], v[118:121]
	v_mfma_f32_16x16x32_bf16 v[118:121], v[158:161], v[208:211], v[118:121]
	v_mfma_f32_16x16x32_bf16 v[110:113], v[162:165], v[204:207], v[110:113]
	v_mfma_f32_16x16x32_bf16 v[110:113], v[166:169], v[208:211], v[110:113]
	v_mfma_f32_16x16x32_bf16 v[102:105], v[154:157], v[214:217], v[102:105]
	v_mfma_f32_16x16x32_bf16 v[102:105], v[158:161], v[218:221], v[102:105]
	v_mfma_f32_16x16x32_bf16 v[94:97], v[162:165], v[214:217], v[94:97]
	v_mfma_f32_16x16x32_bf16 v[94:97], v[166:169], v[218:221], v[94:97]
	v_mfma_f32_16x16x32_bf16 v[86:89], v[154:157], v[222:225], v[86:89]
	v_mfma_f32_16x16x32_bf16 v[86:89], v[158:161], v[226:229], v[86:89]
	v_mfma_f32_16x16x32_bf16 v[78:81], v[162:165], v[222:225], v[78:81]
	v_mfma_f32_16x16x32_bf16 v[78:81], v[166:169], v[226:229], v[78:81]
	v_mfma_f32_16x16x32_bf16 v[114:117], v[170:173], v[196:199], v[114:117]
	v_mfma_f32_16x16x32_bf16 v[114:117], v[174:177], v[200:203], v[114:117]
	v_mfma_f32_16x16x32_bf16 v[106:109], v[188:191], v[196:199], v[106:109]
	v_mfma_f32_16x16x32_bf16 v[106:109], v[192:195], v[200:203], v[106:109]
	v_mfma_f32_16x16x32_bf16 v[98:101], v[170:173], v[204:207], v[98:101]
	v_mfma_f32_16x16x32_bf16 v[98:101], v[174:177], v[208:211], v[98:101]
	v_mfma_f32_16x16x32_bf16 v[90:93], v[188:191], v[204:207], v[90:93]
	v_mfma_f32_16x16x32_bf16 v[90:93], v[192:195], v[208:211], v[90:93]
	v_mfma_f32_16x16x32_bf16 v[82:85], v[170:173], v[214:217], v[82:85]
	v_mfma_f32_16x16x32_bf16 v[82:85], v[174:177], v[218:221], v[82:85]
	v_mfma_f32_16x16x32_bf16 v[74:77], v[188:191], v[214:217], v[74:77]
	v_mfma_f32_16x16x32_bf16 v[74:77], v[192:195], v[218:221], v[74:77]
	v_mfma_f32_16x16x32_bf16 v[70:73], v[170:173], v[222:225], v[70:73]
	v_mfma_f32_16x16x32_bf16 v[70:73], v[174:177], v[226:229], v[70:73]
	v_mfma_f32_16x16x32_bf16 v[66:69], v[188:191], v[222:225], v[66:69]
	v_mfma_f32_16x16x32_bf16 v[66:69], v[192:195], v[226:229], v[66:69]
	s_barrier
	s_add_i32 s69, s54, s3
	s_mov_b32 m0, s69
	ds_read_b128 v[196:199], v153 offset:16384
	ds_read_b128 v[200:203], v153 offset:17408
	ds_read_b128 v[204:207], v153 offset:18432
	ds_read_b128 v[208:211], v153 offset:19456
	ds_read_b128 v[214:217], v153 offset:20480
	ds_read_b128 v[218:221], v153 offset:21504
	ds_read_b128 v[222:225], v153 offset:22528
	ds_read_b128 v[226:229], v153 offset:23552
	global_load_lds_dwordx4 v136, s[42:43]
	s_add_i32 m0, s69, 0x2000
	s_add_u32 s70, s42, 0x108000
	s_addc_u32 s71, s43, 0
	s_add_i32 s69, s55, s3
	global_load_lds_dwordx4 v140, s[42:43]
	s_mov_b32 m0, s69
	s_nop 0
	global_load_lds_dwordx4 v136, s[70:71]
	s_add_i32 m0, s69, 0x2000
	s_nop 0
	global_load_lds_dwordx4 v140, s[70:71]
	s_mov_b32 m0, s47
	s_nop 0
	global_load_lds_dwordx4 v134, s[44:45]
	s_mov_b32 m0, s48
	s_nop 0
	global_load_lds_dwordx4 v138, s[44:45]
	s_waitcnt vmcnt(8)
	s_waitcnt lgkmcnt(0)
	s_barrier
	s_waitcnt lgkmcnt(0)
	v_mfma_f32_16x16x32_bf16 v[62:65], v[154:157], v[196:199], v[62:65]
	v_mfma_f32_16x16x32_bf16 v[62:65], v[158:161], v[200:203], v[62:65]
	v_mfma_f32_16x16x32_bf16 v[58:61], v[162:165], v[196:199], v[58:61]
	v_mfma_f32_16x16x32_bf16 v[58:61], v[166:169], v[200:203], v[58:61]
	v_mfma_f32_16x16x32_bf16 v[54:57], v[154:157], v[204:207], v[54:57]
	v_mfma_f32_16x16x32_bf16 v[54:57], v[158:161], v[208:211], v[54:57]
	v_mfma_f32_16x16x32_bf16 v[46:49], v[162:165], v[204:207], v[46:49]
	v_mfma_f32_16x16x32_bf16 v[46:49], v[166:169], v[208:211], v[46:49]
	v_mfma_f32_16x16x32_bf16 v[38:41], v[154:157], v[214:217], v[38:41]
	v_mfma_f32_16x16x32_bf16 v[38:41], v[158:161], v[218:221], v[38:41]
	v_mfma_f32_16x16x32_bf16 v[30:33], v[162:165], v[214:217], v[30:33]
	v_mfma_f32_16x16x32_bf16 v[30:33], v[166:169], v[218:221], v[30:33]
	v_mfma_f32_16x16x32_bf16 v[22:25], v[154:157], v[222:225], v[22:25]
	v_mfma_f32_16x16x32_bf16 v[22:25], v[158:161], v[226:229], v[22:25]
	v_mfma_f32_16x16x32_bf16 v[14:17], v[162:165], v[222:225], v[14:17]
	v_mfma_f32_16x16x32_bf16 v[14:17], v[166:169], v[226:229], v[14:17]
	v_mfma_f32_16x16x32_bf16 v[50:53], v[170:173], v[196:199], v[50:53]
	v_mfma_f32_16x16x32_bf16 v[50:53], v[174:177], v[200:203], v[50:53]
	v_mfma_f32_16x16x32_bf16 v[42:45], v[188:191], v[196:199], v[42:45]
	v_mfma_f32_16x16x32_bf16 v[42:45], v[192:195], v[200:203], v[42:45]
	v_mfma_f32_16x16x32_bf16 v[34:37], v[170:173], v[204:207], v[34:37]
	v_mfma_f32_16x16x32_bf16 v[34:37], v[174:177], v[208:211], v[34:37]
	v_mfma_f32_16x16x32_bf16 v[26:29], v[188:191], v[204:207], v[26:29]
	v_mfma_f32_16x16x32_bf16 v[26:29], v[192:195], v[208:211], v[26:29]
	v_mfma_f32_16x16x32_bf16 v[18:21], v[170:173], v[214:217], v[18:21]
	v_mfma_f32_16x16x32_bf16 v[18:21], v[174:177], v[218:221], v[18:21]
	v_mfma_f32_16x16x32_bf16 v[10:13], v[188:191], v[214:217], v[10:13]
	v_mfma_f32_16x16x32_bf16 v[10:13], v[192:195], v[218:221], v[10:13]
	v_mfma_f32_16x16x32_bf16 v[6:9], v[170:173], v[222:225], v[6:9]
	v_mfma_f32_16x16x32_bf16 v[6:9], v[174:177], v[226:229], v[6:9]
	v_mfma_f32_16x16x32_bf16 v[2:5], v[188:191], v[222:225], v[2:5]
	v_mfma_f32_16x16x32_bf16 v[2:5], v[192:195], v[226:229], v[2:5]
	s_barrier
	s_add_i32 s69, 0, 0x18000
	s_add_i32 s70, 0, 0x1c000
	v_add_u32_e32 v166, s69, v133
	v_add_u32_e32 v187, s70, v133
	ds_read_b128 v[154:157], v166
	ds_read_b128 v[158:161], v166 offset:1024
	ds_read_b128 v[162:165], v166 offset:2048
	ds_read_b128 v[166:169], v166 offset:3072
	ds_read_b128 v[170:173], v187
	ds_read_b128 v[174:177], v187 offset:1024
	ds_read_b128 v[188:191], v187 offset:2048
	ds_read_b128 v[192:195], v187 offset:3072
	s_add_u32 s44, s44, 0x108000
	s_addc_u32 s45, s45, 0
	s_mov_b32 m0, s49
	ds_read_b128 v[196:199], v153 offset:32768
	ds_read_b128 v[200:203], v153 offset:33792
	ds_read_b128 v[204:207], v153 offset:34816
	ds_read_b128 v[208:211], v153 offset:35840
	ds_read_b128 v[214:217], v153 offset:36864
	ds_read_b128 v[218:221], v153 offset:37888
	ds_read_b128 v[222:225], v153 offset:38912
	ds_read_b128 v[226:229], v153 offset:39936
	global_load_lds_dwordx4 v134, s[44:45]
	s_mov_b32 m0, s50
	s_nop 0
	global_load_lds_dwordx4 v138, s[44:45]
	s_waitcnt vmcnt(8)
	s_waitcnt lgkmcnt(0)
	s_barrier
	s_waitcnt lgkmcnt(0)
	v_mfma_f32_16x16x32_bf16 v[126:129], v[154:157], v[196:199], v[126:129]
	v_mfma_f32_16x16x32_bf16 v[126:129], v[158:161], v[200:203], v[126:129]
	v_mfma_f32_16x16x32_bf16 v[122:125], v[162:165], v[196:199], v[122:125]
	v_mfma_f32_16x16x32_bf16 v[122:125], v[166:169], v[200:203], v[122:125]
	v_mfma_f32_16x16x32_bf16 v[118:121], v[154:157], v[204:207], v[118:121]
	v_mfma_f32_16x16x32_bf16 v[118:121], v[158:161], v[208:211], v[118:121]
	v_mfma_f32_16x16x32_bf16 v[110:113], v[162:165], v[204:207], v[110:113]
	v_mfma_f32_16x16x32_bf16 v[110:113], v[166:169], v[208:211], v[110:113]
	v_mfma_f32_16x16x32_bf16 v[102:105], v[154:157], v[214:217], v[102:105]
	v_mfma_f32_16x16x32_bf16 v[102:105], v[158:161], v[218:221], v[102:105]
	v_mfma_f32_16x16x32_bf16 v[94:97], v[162:165], v[214:217], v[94:97]
	v_mfma_f32_16x16x32_bf16 v[94:97], v[166:169], v[218:221], v[94:97]
	v_mfma_f32_16x16x32_bf16 v[86:89], v[154:157], v[222:225], v[86:89]
	v_mfma_f32_16x16x32_bf16 v[86:89], v[158:161], v[226:229], v[86:89]
	v_mfma_f32_16x16x32_bf16 v[78:81], v[162:165], v[222:225], v[78:81]
	v_mfma_f32_16x16x32_bf16 v[78:81], v[166:169], v[226:229], v[78:81]
	v_mfma_f32_16x16x32_bf16 v[114:117], v[170:173], v[196:199], v[114:117]
	v_mfma_f32_16x16x32_bf16 v[114:117], v[174:177], v[200:203], v[114:117]
	v_mfma_f32_16x16x32_bf16 v[106:109], v[188:191], v[196:199], v[106:109]
	v_mfma_f32_16x16x32_bf16 v[106:109], v[192:195], v[200:203], v[106:109]
	v_mfma_f32_16x16x32_bf16 v[98:101], v[170:173], v[204:207], v[98:101]
	v_mfma_f32_16x16x32_bf16 v[98:101], v[174:177], v[208:211], v[98:101]
	v_mfma_f32_16x16x32_bf16 v[90:93], v[188:191], v[204:207], v[90:93]
	v_mfma_f32_16x16x32_bf16 v[90:93], v[192:195], v[208:211], v[90:93]
	v_mfma_f32_16x16x32_bf16 v[82:85], v[170:173], v[214:217], v[82:85]
	v_mfma_f32_16x16x32_bf16 v[82:85], v[174:177], v[218:221], v[82:85]
	v_mfma_f32_16x16x32_bf16 v[74:77], v[188:191], v[214:217], v[74:77]
	v_mfma_f32_16x16x32_bf16 v[74:77], v[192:195], v[218:221], v[74:77]
	v_mfma_f32_16x16x32_bf16 v[70:73], v[170:173], v[222:225], v[70:73]
	v_mfma_f32_16x16x32_bf16 v[70:73], v[174:177], v[226:229], v[70:73]
	v_mfma_f32_16x16x32_bf16 v[66:69], v[188:191], v[222:225], v[66:69]
	v_mfma_f32_16x16x32_bf16 v[66:69], v[192:195], v[226:229], v[66:69]
	s_barrier
	s_add_i32 s44, s69, s3
	s_add_u32 s42, s42, 0x80
	s_addc_u32 s43, s43, 0
	s_mov_b32 m0, s44
	ds_read_b128 v[196:199], v153 offset:49152
	ds_read_b128 v[200:203], v153 offset:50176
	ds_read_b128 v[204:207], v153 offset:51200
	ds_read_b128 v[208:211], v153 offset:52224
	ds_read_b128 v[214:217], v153 offset:53248
	ds_read_b128 v[218:221], v153 offset:54272
	ds_read_b128 v[222:225], v153 offset:55296
	ds_read_b128 v[226:229], v153 offset:56320
	global_load_lds_dwordx4 v136, s[42:43]
	s_add_i32 m0, s44, 0x2000
	s_add_i32 s44, s70, s3
	global_load_lds_dwordx4 v140, s[42:43]
	s_add_u32 s42, s42, 0x108000
	s_addc_u32 s43, s43, 0
	s_mov_b32 m0, s44
	s_nop 0
	global_load_lds_dwordx4 v136, s[42:43]
	s_add_i32 m0, s44, 0x2000
	s_nop 0
	global_load_lds_dwordx4 v140, s[42:43]
	s_mov_b32 m0, s52
	s_nop 0
	global_load_lds_dwordx4 v134, s[40:41]
	s_mov_b32 m0, s53
	s_nop 0
	global_load_lds_dwordx4 v138, s[40:41]
	s_waitcnt vmcnt(8)
	s_waitcnt lgkmcnt(0)
	s_barrier
	s_waitcnt lgkmcnt(0)
	v_mfma_f32_16x16x32_bf16 v[62:65], v[154:157], v[196:199], v[62:65]
	v_mfma_f32_16x16x32_bf16 v[62:65], v[158:161], v[200:203], v[62:65]
	v_mfma_f32_16x16x32_bf16 v[58:61], v[162:165], v[196:199], v[58:61]
	v_mfma_f32_16x16x32_bf16 v[58:61], v[166:169], v[200:203], v[58:61]
	v_mfma_f32_16x16x32_bf16 v[54:57], v[154:157], v[204:207], v[54:57]
	v_mfma_f32_16x16x32_bf16 v[54:57], v[158:161], v[208:211], v[54:57]
	v_mfma_f32_16x16x32_bf16 v[46:49], v[162:165], v[204:207], v[46:49]
	v_mfma_f32_16x16x32_bf16 v[46:49], v[166:169], v[208:211], v[46:49]
	v_mfma_f32_16x16x32_bf16 v[38:41], v[154:157], v[214:217], v[38:41]
	v_mfma_f32_16x16x32_bf16 v[38:41], v[158:161], v[218:221], v[38:41]
	v_mfma_f32_16x16x32_bf16 v[30:33], v[162:165], v[214:217], v[30:33]
	v_mfma_f32_16x16x32_bf16 v[30:33], v[166:169], v[218:221], v[30:33]
	v_mfma_f32_16x16x32_bf16 v[22:25], v[154:157], v[222:225], v[22:25]
	v_mfma_f32_16x16x32_bf16 v[22:25], v[158:161], v[226:229], v[22:25]
	v_mfma_f32_16x16x32_bf16 v[14:17], v[162:165], v[222:225], v[14:17]
	v_mfma_f32_16x16x32_bf16 v[14:17], v[166:169], v[226:229], v[14:17]
	v_mfma_f32_16x16x32_bf16 v[50:53], v[170:173], v[196:199], v[50:53]
	v_mfma_f32_16x16x32_bf16 v[50:53], v[174:177], v[200:203], v[50:53]
	v_mfma_f32_16x16x32_bf16 v[42:45], v[188:191], v[196:199], v[42:45]
	v_mfma_f32_16x16x32_bf16 v[42:45], v[192:195], v[200:203], v[42:45]
	v_mfma_f32_16x16x32_bf16 v[34:37], v[170:173], v[204:207], v[34:37]
	v_mfma_f32_16x16x32_bf16 v[34:37], v[174:177], v[208:211], v[34:37]
	v_mfma_f32_16x16x32_bf16 v[26:29], v[188:191], v[204:207], v[26:29]
	v_mfma_f32_16x16x32_bf16 v[26:29], v[192:195], v[208:211], v[26:29]
	v_mfma_f32_16x16x32_bf16 v[18:21], v[170:173], v[214:217], v[18:21]
	v_mfma_f32_16x16x32_bf16 v[18:21], v[174:177], v[218:221], v[18:21]
	v_mfma_f32_16x16x32_bf16 v[10:13], v[188:191], v[214:217], v[10:13]
	v_mfma_f32_16x16x32_bf16 v[10:13], v[192:195], v[218:221], v[10:13]
	v_mfma_f32_16x16x32_bf16 v[6:9], v[170:173], v[222:225], v[6:9]
	v_mfma_f32_16x16x32_bf16 v[6:9], v[174:177], v[226:229], v[6:9]
	v_mfma_f32_16x16x32_bf16 v[2:5], v[188:191], v[222:225], v[2:5]
	v_mfma_f32_16x16x32_bf16 v[2:5], v[192:195], v[226:229], v[2:5]
	s_barrier
	s_add_i32 s68, s68, 2
	s_add_u32 s38, s38, 0x100
	s_addc_u32 s39, s39, 0
	s_cmp_gt_u32 s68, 61
	s_cbranch_scc0 .LBB0_101
	s_and_b64 vcc, exec, s[20:21]
	s_cbranch_vccz .LBB0_104
	s_barrier

.LBB0_235:
	ds_read_b128 v[156:159], v150
	ds_read_b128 v[160:163], v150 offset:1024
	ds_read_b128 v[164:167], v150 offset:2048
	ds_read_b128 v[168:171], v150 offset:3072
	ds_read_b128 v[172:175], v151
	ds_read_b128 v[176:179], v151 offset:1024
	ds_read_b128 v[180:183], v151 offset:2048
	ds_read_b128 v[184:187], v151 offset:3072
	s_add_u32 s36, s4, s34
	s_addc_u32 s37, s5, s35
	s_add_u32 s40, s36, 0x100
	s_addc_u32 s41, s37, 0
	s_add_u32 s38, s62, s34
	s_addc_u32 s39, s63, s35
	s_add_u32 s36, s36, 0x180
	s_addc_u32 s37, s37, 0
	s_cmpk_eq_i32 s34, 0x1f00
	s_cselect_b32 s37, s61, s37
	s_cselect_b32 s36, s60, s36
	s_cselect_b32 s39, s31, s39
	s_cselect_b32 s38, s30, s38
	s_cselect_b32 s41, s23, s41
	s_cselect_b32 s40, s22, s40
	s_mov_b32 m0, s46
	v_lshl_add_u64 v[222:223], v[146:147], 0, s[34:35]
	ds_read_b128 v[188:191], v152
	ds_read_b128 v[192:195], v152 offset:1024
	ds_read_b128 v[196:199], v152 offset:2048
	ds_read_b128 v[200:203], v152 offset:3072
	ds_read_b128 v[204:207], v152 offset:4096
	ds_read_b128 v[208:211], v152 offset:5120
	ds_read_b128 v[214:217], v152 offset:6144
	ds_read_b128 v[218:221], v152 offset:7168
	global_load_lds_dwordx4 v[222:223], off
	v_lshl_add_u64 v[222:223], v[148:149], 0, s[34:35]
	s_mov_b32 m0, s47
	s_nop 0
	global_load_lds_dwordx4 v[222:223], off
	s_waitcnt vmcnt(8)
	s_waitcnt lgkmcnt(0)
	s_barrier
	s_waitcnt lgkmcnt(0)
	v_mfma_f32_16x16x32_bf16 v[126:129], v[156:159], v[188:191], v[126:129]
	v_mfma_f32_16x16x32_bf16 v[126:129], v[160:163], v[192:195], v[126:129]
	v_mfma_f32_16x16x32_bf16 v[122:125], v[164:167], v[188:191], v[122:125]
	v_mfma_f32_16x16x32_bf16 v[122:125], v[168:171], v[192:195], v[122:125]
	v_mfma_f32_16x16x32_bf16 v[110:113], v[156:159], v[196:199], v[110:113]
	v_mfma_f32_16x16x32_bf16 v[110:113], v[160:163], v[200:203], v[110:113]
	v_mfma_f32_16x16x32_bf16 v[106:109], v[164:167], v[196:199], v[106:109]
	v_mfma_f32_16x16x32_bf16 v[106:109], v[168:171], v[200:203], v[106:109]
	v_mfma_f32_16x16x32_bf16 v[94:97], v[156:159], v[204:207], v[94:97]
	v_mfma_f32_16x16x32_bf16 v[94:97], v[160:163], v[208:211], v[94:97]
	v_mfma_f32_16x16x32_bf16 v[90:93], v[164:167], v[204:207], v[90:93]
	v_mfma_f32_16x16x32_bf16 v[90:93], v[168:171], v[208:211], v[90:93]
	v_mfma_f32_16x16x32_bf16 v[78:81], v[156:159], v[214:217], v[78:81]
	v_mfma_f32_16x16x32_bf16 v[78:81], v[160:163], v[218:221], v[78:81]
	v_mfma_f32_16x16x32_bf16 v[74:77], v[164:167], v[214:217], v[74:77]
	v_mfma_f32_16x16x32_bf16 v[74:77], v[168:171], v[218:221], v[74:77]
	v_mfma_f32_16x16x32_bf16 v[118:121], v[172:175], v[188:191], v[118:121]
	v_mfma_f32_16x16x32_bf16 v[118:121], v[176:179], v[192:195], v[118:121]
	v_mfma_f32_16x16x32_bf16 v[114:117], v[180:183], v[188:191], v[114:117]
	v_mfma_f32_16x16x32_bf16 v[114:117], v[184:187], v[192:195], v[114:117]
	v_mfma_f32_16x16x32_bf16 v[102:105], v[172:175], v[196:199], v[102:105]
	v_mfma_f32_16x16x32_bf16 v[102:105], v[176:179], v[200:203], v[102:105]
	v_mfma_f32_16x16x32_bf16 v[98:101], v[180:183], v[196:199], v[98:101]
	v_mfma_f32_16x16x32_bf16 v[98:101], v[184:187], v[200:203], v[98:101]
	v_mfma_f32_16x16x32_bf16 v[86:89], v[172:175], v[204:207], v[86:89]
	v_mfma_f32_16x16x32_bf16 v[86:89], v[176:179], v[208:211], v[86:89]
	v_mfma_f32_16x16x32_bf16 v[82:85], v[180:183], v[204:207], v[82:85]
	v_mfma_f32_16x16x32_bf16 v[82:85], v[184:187], v[208:211], v[82:85]
	v_mfma_f32_16x16x32_bf16 v[70:73], v[172:175], v[214:217], v[70:73]
	v_mfma_f32_16x16x32_bf16 v[70:73], v[176:179], v[218:221], v[70:73]
	v_mfma_f32_16x16x32_bf16 v[66:69], v[180:183], v[214:217], v[66:69]
	v_mfma_f32_16x16x32_bf16 v[66:69], v[184:187], v[218:221], v[66:69]
	s_barrier
	s_mov_b32 m0, s48
	s_add_u32 s66, s38, 0x108000
	ds_read_b128 v[188:191], v152 offset:16384
	ds_read_b128 v[192:195], v152 offset:17408
	ds_read_b128 v[196:199], v152 offset:18432
	ds_read_b128 v[200:203], v152 offset:19456
	ds_read_b128 v[204:207], v152 offset:20480
	ds_read_b128 v[208:211], v152 offset:21504
	ds_read_b128 v[214:217], v152 offset:22528
	ds_read_b128 v[218:221], v152 offset:23552
	global_load_lds_dwordx4 v132, s[38:39]
	s_mov_b32 m0, s49
	s_addc_u32 s67, s39, 0
	global_load_lds_dwordx4 v136, s[38:39]
	s_mov_b32 m0, s50
	s_nop 0
	global_load_lds_dwordx4 v132, s[66:67]
	s_mov_b32 m0, s51
	s_nop 0
	global_load_lds_dwordx4 v136, s[66:67]
	s_mov_b32 m0, s3
	s_nop 0
	global_load_lds_dwordx4 v130, s[40:41]
	s_mov_b32 m0, s33
	s_nop 0
	global_load_lds_dwordx4 v134, s[40:41]
	s_waitcnt vmcnt(8)
	s_waitcnt lgkmcnt(0)
	s_barrier
	s_waitcnt lgkmcnt(0)
	v_mfma_f32_16x16x32_bf16 v[62:65], v[156:159], v[188:191], v[62:65]
	v_mfma_f32_16x16x32_bf16 v[62:65], v[160:163], v[192:195], v[62:65]
	v_mfma_f32_16x16x32_bf16 v[58:61], v[164:167], v[188:191], v[58:61]
	v_mfma_f32_16x16x32_bf16 v[58:61], v[168:171], v[192:195], v[58:61]
	v_mfma_f32_16x16x32_bf16 v[46:49], v[156:159], v[196:199], v[46:49]
	v_mfma_f32_16x16x32_bf16 v[46:49], v[160:163], v[200:203], v[46:49]
	v_mfma_f32_16x16x32_bf16 v[42:45], v[164:167], v[196:199], v[42:45]
	v_mfma_f32_16x16x32_bf16 v[42:45], v[168:171], v[200:203], v[42:45]
	v_mfma_f32_16x16x32_bf16 v[30:33], v[156:159], v[204:207], v[30:33]
	v_mfma_f32_16x16x32_bf16 v[30:33], v[160:163], v[208:211], v[30:33]
	v_mfma_f32_16x16x32_bf16 v[26:29], v[164:167], v[204:207], v[26:29]
	v_mfma_f32_16x16x32_bf16 v[26:29], v[168:171], v[208:211], v[26:29]
	v_mfma_f32_16x16x32_bf16 v[14:17], v[156:159], v[214:217], v[14:17]
	v_mfma_f32_16x16x32_bf16 v[14:17], v[160:163], v[218:221], v[14:17]
	v_mfma_f32_16x16x32_bf16 v[10:13], v[164:167], v[214:217], v[10:13]
	v_mfma_f32_16x16x32_bf16 v[10:13], v[168:171], v[218:221], v[10:13]
	v_mfma_f32_16x16x32_bf16 v[54:57], v[172:175], v[188:191], v[54:57]
	v_mfma_f32_16x16x32_bf16 v[54:57], v[176:179], v[192:195], v[54:57]
	v_mfma_f32_16x16x32_bf16 v[50:53], v[180:183], v[188:191], v[50:53]
	v_mfma_f32_16x16x32_bf16 v[50:53], v[184:187], v[192:195], v[50:53]
	v_mfma_f32_16x16x32_bf16 v[38:41], v[172:175], v[196:199], v[38:41]
	v_mfma_f32_16x16x32_bf16 v[38:41], v[176:179], v[200:203], v[38:41]
	v_mfma_f32_16x16x32_bf16 v[34:37], v[180:183], v[196:199], v[34:37]
	v_mfma_f32_16x16x32_bf16 v[34:37], v[184:187], v[200:203], v[34:37]
	v_mfma_f32_16x16x32_bf16 v[22:25], v[172:175], v[204:207], v[22:25]
	v_mfma_f32_16x16x32_bf16 v[22:25], v[176:179], v[208:211], v[22:25]
	v_mfma_f32_16x16x32_bf16 v[18:21], v[180:183], v[204:207], v[18:21]
	v_mfma_f32_16x16x32_bf16 v[18:21], v[184:187], v[208:211], v[18:21]
	v_mfma_f32_16x16x32_bf16 v[6:9], v[172:175], v[214:217], v[6:9]
	v_mfma_f32_16x16x32_bf16 v[6:9], v[176:179], v[218:221], v[6:9]
	v_mfma_f32_16x16x32_bf16 v[2:5], v[180:183], v[214:217], v[2:5]
	v_mfma_f32_16x16x32_bf16 v[2:5], v[184:187], v[218:221], v[2:5]
	s_barrier
	ds_read_b128 v[156:159], v153
	ds_read_b128 v[160:163], v153 offset:1024
	ds_read_b128 v[164:167], v153 offset:2048
	ds_read_b128 v[168:171], v153 offset:3072
	ds_read_b128 v[172:175], v154
	ds_read_b128 v[176:179], v154 offset:1024
	ds_read_b128 v[180:183], v154 offset:2048
	ds_read_b128 v[184:187], v154 offset:3072
	s_add_u32 s40, s40, 0x108000
	s_addc_u32 s41, s41, 0
	s_mov_b32 m0, s42
	ds_read_b128 v[188:191], v152 offset:32768
	ds_read_b128 v[192:195], v152 offset:33792
	ds_read_b128 v[196:199], v152 offset:34816
	ds_read_b128 v[200:203], v152 offset:35840
	ds_read_b128 v[204:207], v152 offset:36864
	ds_read_b128 v[208:211], v152 offset:37888
	ds_read_b128 v[214:217], v152 offset:38912
	ds_read_b128 v[218:221], v152 offset:39936
	global_load_lds_dwordx4 v130, s[40:41]
	s_mov_b32 m0, s43
	s_nop 0
	global_load_lds_dwordx4 v134, s[40:41]
	s_waitcnt vmcnt(8)
	s_waitcnt lgkmcnt(0)
	s_barrier
	s_waitcnt lgkmcnt(0)
	v_mfma_f32_16x16x32_bf16 v[126:129], v[156:159], v[188:191], v[126:129]
	v_mfma_f32_16x16x32_bf16 v[126:129], v[160:163], v[192:195], v[126:129]
	v_mfma_f32_16x16x32_bf16 v[122:125], v[164:167], v[188:191], v[122:125]
	v_mfma_f32_16x16x32_bf16 v[122:125], v[168:171], v[192:195], v[122:125]
	v_mfma_f32_16x16x32_bf16 v[110:113], v[156:159], v[196:199], v[110:113]
	v_mfma_f32_16x16x32_bf16 v[110:113], v[160:163], v[200:203], v[110:113]
	v_mfma_f32_16x16x32_bf16 v[106:109], v[164:167], v[196:199], v[106:109]
	v_mfma_f32_16x16x32_bf16 v[106:109], v[168:171], v[200:203], v[106:109]
	v_mfma_f32_16x16x32_bf16 v[94:97], v[156:159], v[204:207], v[94:97]
	v_mfma_f32_16x16x32_bf16 v[94:97], v[160:163], v[208:211], v[94:97]
	v_mfma_f32_16x16x32_bf16 v[90:93], v[164:167], v[204:207], v[90:93]
	v_mfma_f32_16x16x32_bf16 v[90:93], v[168:171], v[208:211], v[90:93]
	v_mfma_f32_16x16x32_bf16 v[78:81], v[156:159], v[214:217], v[78:81]
	v_mfma_f32_16x16x32_bf16 v[78:81], v[160:163], v[218:221], v[78:81]
	v_mfma_f32_16x16x32_bf16 v[74:77], v[164:167], v[214:217], v[74:77]
	v_mfma_f32_16x16x32_bf16 v[74:77], v[168:171], v[218:221], v[74:77]
	v_mfma_f32_16x16x32_bf16 v[118:121], v[172:175], v[188:191], v[118:121]
	v_mfma_f32_16x16x32_bf16 v[118:121], v[176:179], v[192:195], v[118:121]
	v_mfma_f32_16x16x32_bf16 v[114:117], v[180:183], v[188:191], v[114:117]
	v_mfma_f32_16x16x32_bf16 v[114:117], v[184:187], v[192:195], v[114:117]
	v_mfma_f32_16x16x32_bf16 v[102:105], v[172:175], v[196:199], v[102:105]
	v_mfma_f32_16x16x32_bf16 v[102:105], v[176:179], v[200:203], v[102:105]
	v_mfma_f32_16x16x32_bf16 v[98:101], v[180:183], v[196:199], v[98:101]
	v_mfma_f32_16x16x32_bf16 v[98:101], v[184:187], v[200:203], v[98:101]
	v_mfma_f32_16x16x32_bf16 v[86:89], v[172:175], v[204:207], v[86:89]
	v_mfma_f32_16x16x32_bf16 v[86:89], v[176:179], v[208:211], v[86:89]
	v_mfma_f32_16x16x32_bf16 v[82:85], v[180:183], v[204:207], v[82:85]
	v_mfma_f32_16x16x32_bf16 v[82:85], v[184:187], v[208:211], v[82:85]
	v_mfma_f32_16x16x32_bf16 v[70:73], v[172:175], v[214:217], v[70:73]
	v_mfma_f32_16x16x32_bf16 v[70:73], v[176:179], v[218:221], v[70:73]
	v_mfma_f32_16x16x32_bf16 v[66:69], v[180:183], v[214:217], v[66:69]
	v_mfma_f32_16x16x32_bf16 v[66:69], v[184:187], v[218:221], v[66:69]
	s_barrier
	s_mov_b32 m0, s53
	s_add_u32 s38, s38, 0x80
	s_addc_u32 s39, s39, 0
	ds_read_b128 v[188:191], v152 offset:49152
	ds_read_b128 v[192:195], v152 offset:50176
	ds_read_b128 v[196:199], v152 offset:51200
	ds_read_b128 v[200:203], v152 offset:52224
	ds_read_b128 v[204:207], v152 offset:53248
	ds_read_b128 v[208:211], v152 offset:54272
	ds_read_b128 v[214:217], v152 offset:55296
	ds_read_b128 v[218:221], v152 offset:56320
	global_load_lds_dwordx4 v132, s[38:39]
	s_mov_b32 m0, s54
	s_add_i32 s40, s52, s2
	global_load_lds_dwordx4 v136, s[38:39]
	s_add_u32 s38, s38, 0x108000
	s_addc_u32 s39, s39, 0
	s_mov_b32 m0, s40
	s_nop 0
	global_load_lds_dwordx4 v132, s[38:39]
	s_add_i32 m0, s40, 0x2000
	s_nop 0
	global_load_lds_dwordx4 v136, s[38:39]
	s_mov_b32 m0, s44
	s_nop 0
	global_load_lds_dwordx4 v130, s[36:37]
	s_mov_b32 m0, s45
	s_nop 0
	global_load_lds_dwordx4 v134, s[36:37]
	s_waitcnt vmcnt(8)
	s_waitcnt lgkmcnt(0)
	s_barrier
	s_waitcnt lgkmcnt(0)
	v_mfma_f32_16x16x32_bf16 v[62:65], v[156:159], v[188:191], v[62:65]
	v_mfma_f32_16x16x32_bf16 v[62:65], v[160:163], v[192:195], v[62:65]
	v_mfma_f32_16x16x32_bf16 v[58:61], v[164:167], v[188:191], v[58:61]
	v_mfma_f32_16x16x32_bf16 v[58:61], v[168:171], v[192:195], v[58:61]
	v_mfma_f32_16x16x32_bf16 v[46:49], v[156:159], v[196:199], v[46:49]
	v_mfma_f32_16x16x32_bf16 v[46:49], v[160:163], v[200:203], v[46:49]
	v_mfma_f32_16x16x32_bf16 v[42:45], v[164:167], v[196:199], v[42:45]
	v_mfma_f32_16x16x32_bf16 v[42:45], v[168:171], v[200:203], v[42:45]
	v_mfma_f32_16x16x32_bf16 v[30:33], v[156:159], v[204:207], v[30:33]
	v_mfma_f32_16x16x32_bf16 v[30:33], v[160:163], v[208:211], v[30:33]
	v_mfma_f32_16x16x32_bf16 v[26:29], v[164:167], v[204:207], v[26:29]
	v_mfma_f32_16x16x32_bf16 v[26:29], v[168:171], v[208:211], v[26:29]
	v_mfma_f32_16x16x32_bf16 v[14:17], v[156:159], v[214:217], v[14:17]
	v_mfma_f32_16x16x32_bf16 v[14:17], v[160:163], v[218:221], v[14:17]
	v_mfma_f32_16x16x32_bf16 v[10:13], v[164:167], v[214:217], v[10:13]
	v_mfma_f32_16x16x32_bf16 v[10:13], v[168:171], v[218:221], v[10:13]
	v_mfma_f32_16x16x32_bf16 v[54:57], v[172:175], v[188:191], v[54:57]
	v_mfma_f32_16x16x32_bf16 v[54:57], v[176:179], v[192:195], v[54:57]
	v_mfma_f32_16x16x32_bf16 v[50:53], v[180:183], v[188:191], v[50:53]
	v_mfma_f32_16x16x32_bf16 v[50:53], v[184:187], v[192:195], v[50:53]
	v_mfma_f32_16x16x32_bf16 v[38:41], v[172:175], v[196:199], v[38:41]
	v_mfma_f32_16x16x32_bf16 v[38:41], v[176:179], v[200:203], v[38:41]
	v_mfma_f32_16x16x32_bf16 v[34:37], v[180:183], v[196:199], v[34:37]
	v_mfma_f32_16x16x32_bf16 v[34:37], v[184:187], v[200:203], v[34:37]
	v_mfma_f32_16x16x32_bf16 v[22:25], v[172:175], v[204:207], v[22:25]
	v_mfma_f32_16x16x32_bf16 v[22:25], v[176:179], v[208:211], v[22:25]
	v_mfma_f32_16x16x32_bf16 v[18:21], v[180:183], v[204:207], v[18:21]
	v_mfma_f32_16x16x32_bf16 v[18:21], v[184:187], v[208:211], v[18:21]
	v_mfma_f32_16x16x32_bf16 v[6:9], v[172:175], v[214:217], v[6:9]
	v_mfma_f32_16x16x32_bf16 v[6:9], v[176:179], v[218:221], v[6:9]
	v_mfma_f32_16x16x32_bf16 v[2:5], v[180:183], v[214:217], v[2:5]
	v_mfma_f32_16x16x32_bf16 v[2:5], v[184:187], v[218:221], v[2:5]
	s_barrier
	s_add_i32 s64, s64, 2
	s_add_u32 s34, s34, 0x100
	s_addc_u32 s35, s35, 0
	s_cmp_gt_u32 s64, 61
	s_cbranch_scc0 .LBB0_235
	s_and_b64 vcc, exec, s[20:21]
	s_cbranch_vccz .LBB0_238
	s_barrier

.LBB0_434:
	ds_read_b128 v[134:137], v204
	ds_read_b128 v[138:141], v204 offset:1024
	ds_read_b128 v[142:145], v204 offset:2048
	ds_read_b128 v[146:149], v204 offset:3072
	ds_read_b128 v[150:153], v205
	ds_read_b128 v[154:157], v205 offset:1024
	ds_read_b128 v[158:161], v205 offset:2048
	ds_read_b128 v[162:165], v205 offset:3072
	s_add_u32 s34, s22, s30
	s_addc_u32 s35, s23, s31
	s_add_u32 s38, s34, 0x100
	s_addc_u32 s39, s35, 0
	s_add_u32 s36, s60, s30
	s_addc_u32 s37, s61, s31
	s_add_u32 s34, s34, 0x180
	s_addc_u32 s35, s35, 0
	s_cmpk_eq_i32 s30, 0xb00
	s_cselect_b32 s35, s59, s35
	s_cselect_b32 s34, s58, s34
	s_cselect_b32 s37, s21, s37
	s_cselect_b32 s36, s20, s36
	s_cselect_b32 s39, s17, s39
	s_cselect_b32 s38, s16, s38
	v_lshl_add_u64 v[200:201], v[130:131], 0, s[30:31]
	s_add_i32 m0, s3, 0xc000
	ds_read_b128 v[166:169], v206
	ds_read_b128 v[170:173], v206 offset:1024
	ds_read_b128 v[174:177], v206 offset:2048
	ds_read_b128 v[178:181], v206 offset:3072
	ds_read_b128 v[182:185], v206 offset:4096
	ds_read_b128 v[208:211], v206 offset:5120
	ds_read_b128 v[214:217], v206 offset:6144
	ds_read_b128 v[218:221], v206 offset:7168
	global_load_lds_dwordx4 v[200:201], off
	v_lshl_add_u64 v[200:201], v[132:133], 0, s[30:31]
	s_add_i32 m0, s3, 0xe000
	s_nop 0
	global_load_lds_dwordx4 v[200:201], off
	s_waitcnt vmcnt(8)
	s_waitcnt lgkmcnt(0)
	s_barrier
	s_waitcnt lgkmcnt(0)
	v_mfma_f32_16x16x32_bf16 v[126:129], v[134:137], v[166:169], v[126:129]
	v_mfma_f32_16x16x32_bf16 v[126:129], v[138:141], v[170:173], v[126:129]
	v_mfma_f32_16x16x32_bf16 v[122:125], v[142:145], v[166:169], v[122:125]
	v_mfma_f32_16x16x32_bf16 v[122:125], v[146:149], v[170:173], v[122:125]
	v_mfma_f32_16x16x32_bf16 v[110:113], v[134:137], v[174:177], v[110:113]
	v_mfma_f32_16x16x32_bf16 v[110:113], v[138:141], v[178:181], v[110:113]
	v_mfma_f32_16x16x32_bf16 v[106:109], v[142:145], v[174:177], v[106:109]
	v_mfma_f32_16x16x32_bf16 v[106:109], v[146:149], v[178:181], v[106:109]
	v_mfma_f32_16x16x32_bf16 v[94:97], v[134:137], v[182:185], v[94:97]
	v_mfma_f32_16x16x32_bf16 v[94:97], v[138:141], v[208:211], v[94:97]
	v_mfma_f32_16x16x32_bf16 v[90:93], v[142:145], v[182:185], v[90:93]
	v_mfma_f32_16x16x32_bf16 v[90:93], v[146:149], v[208:211], v[90:93]
	v_mfma_f32_16x16x32_bf16 v[78:81], v[134:137], v[214:217], v[78:81]
	v_mfma_f32_16x16x32_bf16 v[78:81], v[138:141], v[218:221], v[78:81]
	v_mfma_f32_16x16x32_bf16 v[74:77], v[142:145], v[214:217], v[74:77]
	v_mfma_f32_16x16x32_bf16 v[74:77], v[146:149], v[218:221], v[74:77]
	v_mfma_f32_16x16x32_bf16 v[118:121], v[150:153], v[166:169], v[118:121]
	v_mfma_f32_16x16x32_bf16 v[118:121], v[154:157], v[170:173], v[118:121]
	v_mfma_f32_16x16x32_bf16 v[114:117], v[158:161], v[166:169], v[114:117]
	v_mfma_f32_16x16x32_bf16 v[114:117], v[162:165], v[170:173], v[114:117]
	v_mfma_f32_16x16x32_bf16 v[102:105], v[150:153], v[174:177], v[102:105]
	v_mfma_f32_16x16x32_bf16 v[102:105], v[154:157], v[178:181], v[102:105]
	v_mfma_f32_16x16x32_bf16 v[98:101], v[158:161], v[174:177], v[98:101]
	v_mfma_f32_16x16x32_bf16 v[98:101], v[162:165], v[178:181], v[98:101]
	v_mfma_f32_16x16x32_bf16 v[86:89], v[150:153], v[182:185], v[86:89]
	v_mfma_f32_16x16x32_bf16 v[86:89], v[154:157], v[208:211], v[86:89]
	v_mfma_f32_16x16x32_bf16 v[82:85], v[158:161], v[182:185], v[82:85]
	v_mfma_f32_16x16x32_bf16 v[82:85], v[162:165], v[208:211], v[82:85]
	v_mfma_f32_16x16x32_bf16 v[70:73], v[150:153], v[214:217], v[70:73]
	v_mfma_f32_16x16x32_bf16 v[70:73], v[154:157], v[218:221], v[70:73]
	v_mfma_f32_16x16x32_bf16 v[66:69], v[158:161], v[214:217], v[66:69]
	v_mfma_f32_16x16x32_bf16 v[66:69], v[162:165], v[218:221], v[66:69]
	s_barrier
	s_add_i32 s63, s52, s2
	s_mov_b32 m0, s63
	ds_read_b128 v[166:169], v206 offset:16384
	ds_read_b128 v[170:173], v206 offset:17408
	ds_read_b128 v[174:177], v206 offset:18432
	ds_read_b128 v[178:181], v206 offset:19456
	ds_read_b128 v[182:185], v206 offset:20480
	ds_read_b128 v[208:211], v206 offset:21504
	ds_read_b128 v[214:217], v206 offset:22528
	ds_read_b128 v[218:221], v206 offset:23552
	global_load_lds_dwordx4 v188, s[36:37]
	s_add_i32 m0, s63, 0x2000
	s_add_u32 s64, s36, 0x68000
	s_addc_u32 s65, s37, 0
	s_add_i32 s63, s53, s2
	global_load_lds_dwordx4 v192, s[36:37]
	s_mov_b32 m0, s63
	s_nop 0
	global_load_lds_dwordx4 v188, s[64:65]
	s_add_i32 m0, s63, 0x2000
	s_nop 0
	global_load_lds_dwordx4 v192, s[64:65]
	s_mov_b32 m0, s3
	s_nop 0
	global_load_lds_dwordx4 v186, s[38:39]
	s_mov_b32 m0, s33
	s_nop 0
	global_load_lds_dwordx4 v190, s[38:39]
	s_waitcnt vmcnt(8)
	s_waitcnt lgkmcnt(0)
	s_barrier
	s_waitcnt lgkmcnt(0)
	v_mfma_f32_16x16x32_bf16 v[62:65], v[134:137], v[166:169], v[62:65]
	v_mfma_f32_16x16x32_bf16 v[62:65], v[138:141], v[170:173], v[62:65]
	v_mfma_f32_16x16x32_bf16 v[58:61], v[142:145], v[166:169], v[58:61]
	v_mfma_f32_16x16x32_bf16 v[58:61], v[146:149], v[170:173], v[58:61]
	v_mfma_f32_16x16x32_bf16 v[46:49], v[134:137], v[174:177], v[46:49]
	v_mfma_f32_16x16x32_bf16 v[46:49], v[138:141], v[178:181], v[46:49]
	v_mfma_f32_16x16x32_bf16 v[42:45], v[142:145], v[174:177], v[42:45]
	v_mfma_f32_16x16x32_bf16 v[42:45], v[146:149], v[178:181], v[42:45]
	v_mfma_f32_16x16x32_bf16 v[30:33], v[134:137], v[182:185], v[30:33]
	v_mfma_f32_16x16x32_bf16 v[30:33], v[138:141], v[208:211], v[30:33]
	v_mfma_f32_16x16x32_bf16 v[26:29], v[142:145], v[182:185], v[26:29]
	v_mfma_f32_16x16x32_bf16 v[26:29], v[146:149], v[208:211], v[26:29]
	v_mfma_f32_16x16x32_bf16 v[14:17], v[134:137], v[214:217], v[14:17]
	v_mfma_f32_16x16x32_bf16 v[14:17], v[138:141], v[218:221], v[14:17]
	v_mfma_f32_16x16x32_bf16 v[10:13], v[142:145], v[214:217], v[10:13]
	v_mfma_f32_16x16x32_bf16 v[10:13], v[146:149], v[218:221], v[10:13]
	v_mfma_f32_16x16x32_bf16 v[54:57], v[150:153], v[166:169], v[54:57]
	v_mfma_f32_16x16x32_bf16 v[54:57], v[154:157], v[170:173], v[54:57]
	v_mfma_f32_16x16x32_bf16 v[50:53], v[158:161], v[166:169], v[50:53]
	v_mfma_f32_16x16x32_bf16 v[50:53], v[162:165], v[170:173], v[50:53]
	v_mfma_f32_16x16x32_bf16 v[38:41], v[150:153], v[174:177], v[38:41]
	v_mfma_f32_16x16x32_bf16 v[38:41], v[154:157], v[178:181], v[38:41]
	v_mfma_f32_16x16x32_bf16 v[34:37], v[158:161], v[174:177], v[34:37]
	v_mfma_f32_16x16x32_bf16 v[34:37], v[162:165], v[178:181], v[34:37]
	v_mfma_f32_16x16x32_bf16 v[22:25], v[150:153], v[182:185], v[22:25]
	v_mfma_f32_16x16x32_bf16 v[22:25], v[154:157], v[208:211], v[22:25]
	v_mfma_f32_16x16x32_bf16 v[18:21], v[158:161], v[182:185], v[18:21]
	v_mfma_f32_16x16x32_bf16 v[18:21], v[162:165], v[208:211], v[18:21]
	v_mfma_f32_16x16x32_bf16 v[6:9], v[150:153], v[214:217], v[6:9]
	v_mfma_f32_16x16x32_bf16 v[6:9], v[154:157], v[218:221], v[6:9]
	v_mfma_f32_16x16x32_bf16 v[2:5], v[158:161], v[214:217], v[2:5]
	v_mfma_f32_16x16x32_bf16 v[2:5], v[162:165], v[218:221], v[2:5]
	s_barrier
	s_add_i32 s63, 0, 0x18000
	s_add_i32 s64, 0, 0x1c000
	v_add_u32_e32 v146, s63, v202
	v_add_u32_e32 v162, s64, v202
	ds_read_b128 v[134:137], v146
	ds_read_b128 v[138:141], v146 offset:1024
	ds_read_b128 v[142:145], v146 offset:2048
	ds_read_b128 v[146:149], v146 offset:3072
	ds_read_b128 v[150:153], v162
	ds_read_b128 v[154:157], v162 offset:1024
	ds_read_b128 v[158:161], v162 offset:2048
	ds_read_b128 v[162:165], v162 offset:3072
	s_add_u32 s38, s38, 0x188000
	s_addc_u32 s39, s39, 0
	s_mov_b32 m0, s40
	ds_read_b128 v[166:169], v206 offset:32768
	ds_read_b128 v[170:173], v206 offset:33792
	ds_read_b128 v[174:177], v206 offset:34816
	ds_read_b128 v[178:181], v206 offset:35840
	ds_read_b128 v[182:185], v206 offset:36864
	ds_read_b128 v[208:211], v206 offset:37888
	ds_read_b128 v[214:217], v206 offset:38912
	ds_read_b128 v[218:221], v206 offset:39936
	global_load_lds_dwordx4 v186, s[38:39]
	s_mov_b32 m0, s41
	s_nop 0
	global_load_lds_dwordx4 v190, s[38:39]
	s_waitcnt vmcnt(8)
	s_waitcnt lgkmcnt(0)
	s_barrier
	s_waitcnt lgkmcnt(0)
	v_mfma_f32_16x16x32_bf16 v[126:129], v[134:137], v[166:169], v[126:129]
	v_mfma_f32_16x16x32_bf16 v[126:129], v[138:141], v[170:173], v[126:129]
	v_mfma_f32_16x16x32_bf16 v[122:125], v[142:145], v[166:169], v[122:125]
	v_mfma_f32_16x16x32_bf16 v[122:125], v[146:149], v[170:173], v[122:125]
	v_mfma_f32_16x16x32_bf16 v[110:113], v[134:137], v[174:177], v[110:113]
	v_mfma_f32_16x16x32_bf16 v[110:113], v[138:141], v[178:181], v[110:113]
	v_mfma_f32_16x16x32_bf16 v[106:109], v[142:145], v[174:177], v[106:109]
	v_mfma_f32_16x16x32_bf16 v[106:109], v[146:149], v[178:181], v[106:109]
	v_mfma_f32_16x16x32_bf16 v[94:97], v[134:137], v[182:185], v[94:97]
	v_mfma_f32_16x16x32_bf16 v[94:97], v[138:141], v[208:211], v[94:97]
	v_mfma_f32_16x16x32_bf16 v[90:93], v[142:145], v[182:185], v[90:93]
	v_mfma_f32_16x16x32_bf16 v[90:93], v[146:149], v[208:211], v[90:93]
	v_mfma_f32_16x16x32_bf16 v[78:81], v[134:137], v[214:217], v[78:81]
	v_mfma_f32_16x16x32_bf16 v[78:81], v[138:141], v[218:221], v[78:81]
	v_mfma_f32_16x16x32_bf16 v[74:77], v[142:145], v[214:217], v[74:77]
	v_mfma_f32_16x16x32_bf16 v[74:77], v[146:149], v[218:221], v[74:77]
	v_mfma_f32_16x16x32_bf16 v[118:121], v[150:153], v[166:169], v[118:121]
	v_mfma_f32_16x16x32_bf16 v[118:121], v[154:157], v[170:173], v[118:121]
	v_mfma_f32_16x16x32_bf16 v[114:117], v[158:161], v[166:169], v[114:117]
	v_mfma_f32_16x16x32_bf16 v[114:117], v[162:165], v[170:173], v[114:117]
	v_mfma_f32_16x16x32_bf16 v[102:105], v[150:153], v[174:177], v[102:105]
	v_mfma_f32_16x16x32_bf16 v[102:105], v[154:157], v[178:181], v[102:105]
	v_mfma_f32_16x16x32_bf16 v[98:101], v[158:161], v[174:177], v[98:101]
	v_mfma_f32_16x16x32_bf16 v[98:101], v[162:165], v[178:181], v[98:101]
	v_mfma_f32_16x16x32_bf16 v[86:89], v[150:153], v[182:185], v[86:89]
	v_mfma_f32_16x16x32_bf16 v[86:89], v[154:157], v[208:211], v[86:89]
	v_mfma_f32_16x16x32_bf16 v[82:85], v[158:161], v[182:185], v[82:85]
	v_mfma_f32_16x16x32_bf16 v[82:85], v[162:165], v[208:211], v[82:85]
	v_mfma_f32_16x16x32_bf16 v[70:73], v[150:153], v[214:217], v[70:73]
	v_mfma_f32_16x16x32_bf16 v[70:73], v[154:157], v[218:221], v[70:73]
	v_mfma_f32_16x16x32_bf16 v[66:69], v[158:161], v[214:217], v[66:69]
	v_mfma_f32_16x16x32_bf16 v[66:69], v[162:165], v[218:221], v[66:69]
	s_barrier
	s_add_i32 s38, s63, s2
	s_add_u32 s36, s36, 0x80
	s_addc_u32 s37, s37, 0
	s_mov_b32 m0, s38
	ds_read_b128 v[166:169], v206 offset:49152
	ds_read_b128 v[170:173], v206 offset:50176
	ds_read_b128 v[174:177], v206 offset:51200
	ds_read_b128 v[178:181], v206 offset:52224
	ds_read_b128 v[182:185], v206 offset:53248
	ds_read_b128 v[208:211], v206 offset:54272
	ds_read_b128 v[214:217], v206 offset:55296
	ds_read_b128 v[218:221], v206 offset:56320
	global_load_lds_dwordx4 v188, s[36:37]
	s_add_i32 m0, s38, 0x2000
	s_add_i32 s38, s64, s2
	global_load_lds_dwordx4 v192, s[36:37]
	s_add_u32 s36, s36, 0x68000
	s_addc_u32 s37, s37, 0
	s_mov_b32 m0, s38
	s_nop 0
	global_load_lds_dwordx4 v188, s[36:37]
	s_add_i32 m0, s38, 0x2000
	s_nop 0
	global_load_lds_dwordx4 v192, s[36:37]
	s_mov_b32 m0, s50
	s_nop 0
	global_load_lds_dwordx4 v186, s[34:35]
	s_mov_b32 m0, s51
	s_nop 0
	global_load_lds_dwordx4 v190, s[34:35]
	s_waitcnt vmcnt(8)
	s_waitcnt lgkmcnt(0)
	s_barrier
	s_waitcnt lgkmcnt(0)
	v_mfma_f32_16x16x32_bf16 v[62:65], v[134:137], v[166:169], v[62:65]
	v_mfma_f32_16x16x32_bf16 v[62:65], v[138:141], v[170:173], v[62:65]
	v_mfma_f32_16x16x32_bf16 v[58:61], v[142:145], v[166:169], v[58:61]
	v_mfma_f32_16x16x32_bf16 v[58:61], v[146:149], v[170:173], v[58:61]
	v_mfma_f32_16x16x32_bf16 v[46:49], v[134:137], v[174:177], v[46:49]
	v_mfma_f32_16x16x32_bf16 v[46:49], v[138:141], v[178:181], v[46:49]
	v_mfma_f32_16x16x32_bf16 v[42:45], v[142:145], v[174:177], v[42:45]
	v_mfma_f32_16x16x32_bf16 v[42:45], v[146:149], v[178:181], v[42:45]
	v_mfma_f32_16x16x32_bf16 v[30:33], v[134:137], v[182:185], v[30:33]
	v_mfma_f32_16x16x32_bf16 v[30:33], v[138:141], v[208:211], v[30:33]
	v_mfma_f32_16x16x32_bf16 v[26:29], v[142:145], v[182:185], v[26:29]
	v_mfma_f32_16x16x32_bf16 v[26:29], v[146:149], v[208:211], v[26:29]
	v_mfma_f32_16x16x32_bf16 v[14:17], v[134:137], v[214:217], v[14:17]
	v_mfma_f32_16x16x32_bf16 v[14:17], v[138:141], v[218:221], v[14:17]
	v_mfma_f32_16x16x32_bf16 v[10:13], v[142:145], v[214:217], v[10:13]
	v_mfma_f32_16x16x32_bf16 v[10:13], v[146:149], v[218:221], v[10:13]
	v_mfma_f32_16x16x32_bf16 v[54:57], v[150:153], v[166:169], v[54:57]
	v_mfma_f32_16x16x32_bf16 v[54:57], v[154:157], v[170:173], v[54:57]
	v_mfma_f32_16x16x32_bf16 v[50:53], v[158:161], v[166:169], v[50:53]
	v_mfma_f32_16x16x32_bf16 v[50:53], v[162:165], v[170:173], v[50:53]
	v_mfma_f32_16x16x32_bf16 v[38:41], v[150:153], v[174:177], v[38:41]
	v_mfma_f32_16x16x32_bf16 v[38:41], v[154:157], v[178:181], v[38:41]
	v_mfma_f32_16x16x32_bf16 v[34:37], v[158:161], v[174:177], v[34:37]
	v_mfma_f32_16x16x32_bf16 v[34:37], v[162:165], v[178:181], v[34:37]
	v_mfma_f32_16x16x32_bf16 v[22:25], v[150:153], v[182:185], v[22:25]
	v_mfma_f32_16x16x32_bf16 v[22:25], v[154:157], v[208:211], v[22:25]
	v_mfma_f32_16x16x32_bf16 v[18:21], v[158:161], v[182:185], v[18:21]
	v_mfma_f32_16x16x32_bf16 v[18:21], v[162:165], v[208:211], v[18:21]
	v_mfma_f32_16x16x32_bf16 v[6:9], v[150:153], v[214:217], v[6:9]
	v_mfma_f32_16x16x32_bf16 v[6:9], v[154:157], v[218:221], v[6:9]
	v_mfma_f32_16x16x32_bf16 v[2:5], v[158:161], v[214:217], v[2:5]
	v_mfma_f32_16x16x32_bf16 v[2:5], v[162:165], v[218:221], v[2:5]
	s_barrier
	s_add_i32 s62, s62, 2
	s_add_u32 s30, s30, 0x100
	s_addc_u32 s31, s31, 0
	s_cmp_gt_u32 s62, 21
	s_cbranch_scc0 .LBB0_434
	s_and_b64 vcc, exec, s[14:15]
	s_cbranch_vccz .LBB0_437
	s_barrier

.LBB0_519:
	s_add_i32 s39, s56, 0xfffe8000
	s_and_b32 s38, s36, 0x100
	s_and_b32 s39, s39, 0x3e0000
	s_or_b32 s38, s38, s39
	s_add_u32 s57, s34, s38
	s_addc_u32 s59, s35, 0
	s_add_u32 s38, s36, 0x100
	s_addc_u32 s39, s37, 0
	s_add_i32 s41, s56, 0xffff8000
	s_and_b32 s40, s38, 0x100
	s_and_b32 s41, s41, 0x7e0000
	s_or_b32 s40, s41, s40
	s_add_u32 s40, s34, s40
	s_addc_u32 s41, s35, 0
	s_add_u32 s58, s53, s36
	s_addc_u32 s37, s54, s37
	s_add_i32 s42, s36, 0x180
	s_and_b32 s42, s42, 0x180
	s_and_b32 s43, s56, 0x7e0000
	s_or_b32 s42, s43, s42
	s_add_u32 s60, s34, s42
	s_addc_u32 s61, s35, 0
	s_cmpk_eq_i32 s36, 0x3f00
	s_cselect_b32 s43, s1, s41
	s_cselect_b32 s42, s21, s40
	s_cselect_b32 s41, s23, s37
	s_cselect_b32 s40, s22, s58
	s_cselect_b32 s37, s52, s61
	s_cselect_b32 s36, s31, s60
	s_add_i32 s60, 0, 0x10000
	v_add_u32_e32 v1, s60, v199
	ds_read_b128 v[130:133], v1
	ds_read_b128 v[134:137], v1 offset:1024
	ds_read_b128 v[138:141], v1 offset:2048
	ds_read_b128 v[142:145], v1 offset:3072
	ds_read_b128 v[146:149], v201
	ds_read_b128 v[150:153], v201 offset:1024
	ds_read_b128 v[154:157], v201 offset:2048
	ds_read_b128 v[158:161], v201 offset:3072
	s_add_u32 s58, s57, 0x10080
	s_addc_u32 s59, s59, 0
	s_add_i32 m0, s3, 0xc000
	ds_read_b128 v[162:165], v202
	ds_read_b128 v[166:169], v202 offset:1024
	ds_read_b128 v[170:173], v202 offset:2048
	ds_read_b128 v[174:177], v202 offset:3072
	ds_read_b128 v[186:189], v202 offset:4096
	ds_read_b128 v[190:193], v202 offset:5120
	ds_read_b128 v[194:197], v202 offset:6144
	ds_read_b128 v[204:207], v202 offset:7168
	global_load_lds_dwordx4 v178, s[58:59]
	s_add_i32 m0, s3, 0xe000
	s_nop 0
	global_load_lds_dwordx4 v182, s[58:59]
	s_waitcnt vmcnt(8)
	s_waitcnt lgkmcnt(0)
	s_barrier
	s_waitcnt lgkmcnt(0)
	v_mfma_f32_16x16x32_bf16 v[126:129], v[130:133], v[162:165], v[126:129]
	v_mfma_f32_16x16x32_bf16 v[126:129], v[134:137], v[166:169], v[126:129]
	v_mfma_f32_16x16x32_bf16 v[122:125], v[138:141], v[162:165], v[122:125]
	v_mfma_f32_16x16x32_bf16 v[122:125], v[142:145], v[166:169], v[122:125]
	v_mfma_f32_16x16x32_bf16 v[110:113], v[130:133], v[170:173], v[110:113]
	v_mfma_f32_16x16x32_bf16 v[110:113], v[134:137], v[174:177], v[110:113]
	v_mfma_f32_16x16x32_bf16 v[106:109], v[138:141], v[170:173], v[106:109]
	v_mfma_f32_16x16x32_bf16 v[106:109], v[142:145], v[174:177], v[106:109]
	v_mfma_f32_16x16x32_bf16 v[94:97], v[130:133], v[186:189], v[94:97]
	v_mfma_f32_16x16x32_bf16 v[94:97], v[134:137], v[190:193], v[94:97]
	v_mfma_f32_16x16x32_bf16 v[90:93], v[138:141], v[186:189], v[90:93]
	v_mfma_f32_16x16x32_bf16 v[90:93], v[142:145], v[190:193], v[90:93]
	v_mfma_f32_16x16x32_bf16 v[78:81], v[130:133], v[194:197], v[78:81]
	v_mfma_f32_16x16x32_bf16 v[78:81], v[134:137], v[204:207], v[78:81]
	v_mfma_f32_16x16x32_bf16 v[74:77], v[138:141], v[194:197], v[74:77]
	v_mfma_f32_16x16x32_bf16 v[74:77], v[142:145], v[204:207], v[74:77]
	v_mfma_f32_16x16x32_bf16 v[118:121], v[146:149], v[162:165], v[118:121]
	v_mfma_f32_16x16x32_bf16 v[118:121], v[150:153], v[166:169], v[118:121]
	v_mfma_f32_16x16x32_bf16 v[114:117], v[154:157], v[162:165], v[114:117]
	v_mfma_f32_16x16x32_bf16 v[114:117], v[158:161], v[166:169], v[114:117]
	v_mfma_f32_16x16x32_bf16 v[102:105], v[146:149], v[170:173], v[102:105]
	v_mfma_f32_16x16x32_bf16 v[102:105], v[150:153], v[174:177], v[102:105]
	v_mfma_f32_16x16x32_bf16 v[98:101], v[154:157], v[170:173], v[98:101]
	v_mfma_f32_16x16x32_bf16 v[98:101], v[158:161], v[174:177], v[98:101]
	v_mfma_f32_16x16x32_bf16 v[86:89], v[146:149], v[186:189], v[86:89]
	v_mfma_f32_16x16x32_bf16 v[86:89], v[150:153], v[190:193], v[86:89]
	v_mfma_f32_16x16x32_bf16 v[82:85], v[154:157], v[186:189], v[82:85]
	v_mfma_f32_16x16x32_bf16 v[82:85], v[158:161], v[190:193], v[82:85]
	v_mfma_f32_16x16x32_bf16 v[70:73], v[146:149], v[194:197], v[70:73]
	v_mfma_f32_16x16x32_bf16 v[70:73], v[150:153], v[204:207], v[70:73]
	v_mfma_f32_16x16x32_bf16 v[66:69], v[154:157], v[194:197], v[66:69]
	v_mfma_f32_16x16x32_bf16 v[66:69], v[158:161], v[204:207], v[66:69]
	s_barrier
	s_add_i32 s57, s60, s2
	v_lshl_add_u64 v[208:209], s[40:41], 0, v[180:181]
	s_mov_b32 m0, s57
	ds_read_b128 v[162:165], v202 offset:16384
	ds_read_b128 v[166:169], v202 offset:17408
	ds_read_b128 v[170:173], v202 offset:18432
	ds_read_b128 v[174:177], v202 offset:19456
	ds_read_b128 v[186:189], v202 offset:20480
	ds_read_b128 v[190:193], v202 offset:21504
	ds_read_b128 v[194:197], v202 offset:22528
	ds_read_b128 v[204:207], v202 offset:23552
	global_load_lds_dwordx4 v[208:209], off
	s_add_i32 m0, s57, 0x2000
	s_add_u32 s58, s40, 0x208000
	v_lshl_add_u64 v[210:211], s[40:41], 0, v[184:185]
	s_addc_u32 s59, s41, 0
	s_add_i32 s57, s49, s2
	global_load_lds_dwordx4 v[210:211], off
	s_mov_b32 m0, s57
	s_nop 0
	global_load_lds_dwordx4 v180, s[58:59]
	s_add_i32 m0, s57, 0x2000
	s_nop 0
	global_load_lds_dwordx4 v184, s[58:59]
	s_mov_b32 m0, s3
	s_nop 0
	global_load_lds_dwordx4 v178, s[42:43]
	s_mov_b32 m0, s33
	s_nop 0
	global_load_lds_dwordx4 v182, s[42:43]
	s_waitcnt vmcnt(8)
	s_waitcnt lgkmcnt(0)
	s_barrier
	s_waitcnt lgkmcnt(0)
	v_mfma_f32_16x16x32_bf16 v[62:65], v[130:133], v[162:165], v[62:65]
	v_mfma_f32_16x16x32_bf16 v[62:65], v[134:137], v[166:169], v[62:65]
	v_mfma_f32_16x16x32_bf16 v[58:61], v[138:141], v[162:165], v[58:61]
	v_mfma_f32_16x16x32_bf16 v[58:61], v[142:145], v[166:169], v[58:61]
	v_mfma_f32_16x16x32_bf16 v[46:49], v[130:133], v[170:173], v[46:49]
	v_mfma_f32_16x16x32_bf16 v[46:49], v[134:137], v[174:177], v[46:49]
	v_mfma_f32_16x16x32_bf16 v[42:45], v[138:141], v[170:173], v[42:45]
	v_mfma_f32_16x16x32_bf16 v[42:45], v[142:145], v[174:177], v[42:45]
	v_mfma_f32_16x16x32_bf16 v[30:33], v[130:133], v[186:189], v[30:33]
	v_mfma_f32_16x16x32_bf16 v[30:33], v[134:137], v[190:193], v[30:33]
	v_mfma_f32_16x16x32_bf16 v[26:29], v[138:141], v[186:189], v[26:29]
	v_mfma_f32_16x16x32_bf16 v[26:29], v[142:145], v[190:193], v[26:29]
	v_mfma_f32_16x16x32_bf16 v[14:17], v[130:133], v[194:197], v[14:17]
	v_mfma_f32_16x16x32_bf16 v[14:17], v[134:137], v[204:207], v[14:17]
	v_mfma_f32_16x16x32_bf16 v[10:13], v[138:141], v[194:197], v[10:13]
	v_mfma_f32_16x16x32_bf16 v[10:13], v[142:145], v[204:207], v[10:13]
	v_mfma_f32_16x16x32_bf16 v[54:57], v[146:149], v[162:165], v[54:57]
	v_mfma_f32_16x16x32_bf16 v[54:57], v[150:153], v[166:169], v[54:57]
	v_mfma_f32_16x16x32_bf16 v[50:53], v[154:157], v[162:165], v[50:53]
	v_mfma_f32_16x16x32_bf16 v[50:53], v[158:161], v[166:169], v[50:53]
	v_mfma_f32_16x16x32_bf16 v[38:41], v[146:149], v[170:173], v[38:41]
	v_mfma_f32_16x16x32_bf16 v[38:41], v[150:153], v[174:177], v[38:41]
	v_mfma_f32_16x16x32_bf16 v[34:37], v[154:157], v[170:173], v[34:37]
	v_mfma_f32_16x16x32_bf16 v[34:37], v[158:161], v[174:177], v[34:37]
	v_mfma_f32_16x16x32_bf16 v[22:25], v[146:149], v[186:189], v[22:25]
	v_mfma_f32_16x16x32_bf16 v[22:25], v[150:153], v[190:193], v[22:25]
	v_mfma_f32_16x16x32_bf16 v[18:21], v[154:157], v[186:189], v[18:21]
	v_mfma_f32_16x16x32_bf16 v[18:21], v[158:161], v[190:193], v[18:21]
	v_mfma_f32_16x16x32_bf16 v[6:9], v[146:149], v[194:197], v[6:9]
	v_mfma_f32_16x16x32_bf16 v[6:9], v[150:153], v[204:207], v[6:9]
	v_mfma_f32_16x16x32_bf16 v[2:5], v[154:157], v[194:197], v[2:5]
	v_mfma_f32_16x16x32_bf16 v[2:5], v[158:161], v[204:207], v[2:5]
	s_barrier
	s_add_i32 s57, 0, 0x18000
	v_add_u32_e32 v1, s57, v199
	s_add_i32 s58, 0, 0x1c000
	ds_read_b128 v[130:133], v1
	ds_read_b128 v[134:137], v1 offset:1024
	ds_read_b128 v[138:141], v1 offset:2048
	ds_read_b128 v[142:145], v1 offset:3072
	v_add_u32_e32 v1, s58, v199
	ds_read_b128 v[146:149], v1
	ds_read_b128 v[150:153], v1 offset:1024
	ds_read_b128 v[154:157], v1 offset:2048
	ds_read_b128 v[158:161], v1 offset:3072
	s_add_u32 s42, s42, 0x10000
	s_addc_u32 s43, s43, 0
	s_mov_b32 m0, s44
	ds_read_b128 v[162:165], v202 offset:32768
	ds_read_b128 v[166:169], v202 offset:33792
	ds_read_b128 v[170:173], v202 offset:34816
	ds_read_b128 v[174:177], v202 offset:35840
	ds_read_b128 v[186:189], v202 offset:36864
	ds_read_b128 v[190:193], v202 offset:37888
	ds_read_b128 v[194:197], v202 offset:38912
	ds_read_b128 v[204:207], v202 offset:39936
	global_load_lds_dwordx4 v178, s[42:43]
	v_lshl_add_u64 v[214:215], s[42:43], 0, v[182:183]
	s_mov_b32 m0, s45
	s_nop 0
	global_load_lds_dwordx4 v[214:215], off
	s_waitcnt vmcnt(8)
	s_waitcnt lgkmcnt(0)
	s_barrier
	s_waitcnt lgkmcnt(0)
	v_mfma_f32_16x16x32_bf16 v[126:129], v[130:133], v[162:165], v[126:129]
	v_mfma_f32_16x16x32_bf16 v[126:129], v[134:137], v[166:169], v[126:129]
	v_mfma_f32_16x16x32_bf16 v[122:125], v[138:141], v[162:165], v[122:125]
	v_mfma_f32_16x16x32_bf16 v[122:125], v[142:145], v[166:169], v[122:125]
	v_mfma_f32_16x16x32_bf16 v[110:113], v[130:133], v[170:173], v[110:113]
	v_mfma_f32_16x16x32_bf16 v[110:113], v[134:137], v[174:177], v[110:113]
	v_mfma_f32_16x16x32_bf16 v[106:109], v[138:141], v[170:173], v[106:109]
	v_mfma_f32_16x16x32_bf16 v[106:109], v[142:145], v[174:177], v[106:109]
	v_mfma_f32_16x16x32_bf16 v[94:97], v[130:133], v[186:189], v[94:97]
	v_mfma_f32_16x16x32_bf16 v[94:97], v[134:137], v[190:193], v[94:97]
	v_mfma_f32_16x16x32_bf16 v[90:93], v[138:141], v[186:189], v[90:93]
	v_mfma_f32_16x16x32_bf16 v[90:93], v[142:145], v[190:193], v[90:93]
	v_mfma_f32_16x16x32_bf16 v[78:81], v[130:133], v[194:197], v[78:81]
	v_mfma_f32_16x16x32_bf16 v[78:81], v[134:137], v[204:207], v[78:81]
	v_mfma_f32_16x16x32_bf16 v[74:77], v[138:141], v[194:197], v[74:77]
	v_mfma_f32_16x16x32_bf16 v[74:77], v[142:145], v[204:207], v[74:77]
	v_mfma_f32_16x16x32_bf16 v[118:121], v[146:149], v[162:165], v[118:121]
	v_mfma_f32_16x16x32_bf16 v[118:121], v[150:153], v[166:169], v[118:121]
	v_mfma_f32_16x16x32_bf16 v[114:117], v[154:157], v[162:165], v[114:117]
	v_mfma_f32_16x16x32_bf16 v[114:117], v[158:161], v[166:169], v[114:117]
	v_mfma_f32_16x16x32_bf16 v[102:105], v[146:149], v[170:173], v[102:105]
	v_mfma_f32_16x16x32_bf16 v[102:105], v[150:153], v[174:177], v[102:105]
	v_mfma_f32_16x16x32_bf16 v[98:101], v[154:157], v[170:173], v[98:101]
	v_mfma_f32_16x16x32_bf16 v[98:101], v[158:161], v[174:177], v[98:101]
	v_mfma_f32_16x16x32_bf16 v[86:89], v[146:149], v[186:189], v[86:89]
	v_mfma_f32_16x16x32_bf16 v[86:89], v[150:153], v[190:193], v[86:89]
	v_mfma_f32_16x16x32_bf16 v[82:85], v[154:157], v[186:189], v[82:85]
	v_mfma_f32_16x16x32_bf16 v[82:85], v[158:161], v[190:193], v[82:85]
	v_mfma_f32_16x16x32_bf16 v[70:73], v[146:149], v[194:197], v[70:73]
	v_mfma_f32_16x16x32_bf16 v[70:73], v[150:153], v[204:207], v[70:73]
	v_mfma_f32_16x16x32_bf16 v[66:69], v[154:157], v[194:197], v[66:69]
	v_mfma_f32_16x16x32_bf16 v[66:69], v[158:161], v[204:207], v[66:69]
	s_barrier
	s_add_i32 s42, s57, s2
	v_lshl_add_u64 v[208:209], v[208:209], 0, s[16:17]
	s_mov_b32 m0, s42
	ds_read_b128 v[162:165], v202 offset:49152
	ds_read_b128 v[166:169], v202 offset:50176
	ds_read_b128 v[170:173], v202 offset:51200
	ds_read_b128 v[174:177], v202 offset:52224
	ds_read_b128 v[186:189], v202 offset:53248
	ds_read_b128 v[190:193], v202 offset:54272
	ds_read_b128 v[194:197], v202 offset:55296
	ds_read_b128 v[204:207], v202 offset:56320
	global_load_lds_dwordx4 v[208:209], off
	s_add_i32 m0, s42, 0x2000
	s_add_u32 s40, s40, 0x208080
	v_lshl_add_u64 v[208:209], v[210:211], 0, s[16:17]
	s_addc_u32 s41, s41, 0
	s_add_i32 s42, s58, s2
	global_load_lds_dwordx4 v[208:209], off
	s_mov_b32 m0, s42
	s_nop 0
	global_load_lds_dwordx4 v180, s[40:41]
	s_add_i32 m0, s42, 0x2000
	s_nop 0
	global_load_lds_dwordx4 v184, s[40:41]
	s_mov_b32 m0, s47
	s_nop 0
	global_load_lds_dwordx4 v178, s[36:37]
	v_lshl_add_u64 v[208:209], s[36:37], 0, v[182:183]
	s_mov_b32 m0, s48
	s_nop 0
	global_load_lds_dwordx4 v[208:209], off
	s_waitcnt vmcnt(8)
	s_waitcnt lgkmcnt(0)
	s_barrier
	s_waitcnt lgkmcnt(0)
	v_mfma_f32_16x16x32_bf16 v[62:65], v[130:133], v[162:165], v[62:65]
	v_mfma_f32_16x16x32_bf16 v[62:65], v[134:137], v[166:169], v[62:65]
	v_mfma_f32_16x16x32_bf16 v[58:61], v[138:141], v[162:165], v[58:61]
	v_mfma_f32_16x16x32_bf16 v[58:61], v[142:145], v[166:169], v[58:61]
	v_mfma_f32_16x16x32_bf16 v[46:49], v[130:133], v[170:173], v[46:49]
	v_mfma_f32_16x16x32_bf16 v[46:49], v[134:137], v[174:177], v[46:49]
	v_mfma_f32_16x16x32_bf16 v[42:45], v[138:141], v[170:173], v[42:45]
	v_mfma_f32_16x16x32_bf16 v[42:45], v[142:145], v[174:177], v[42:45]
	v_mfma_f32_16x16x32_bf16 v[30:33], v[130:133], v[186:189], v[30:33]
	v_mfma_f32_16x16x32_bf16 v[30:33], v[134:137], v[190:193], v[30:33]
	v_mfma_f32_16x16x32_bf16 v[26:29], v[138:141], v[186:189], v[26:29]
	v_mfma_f32_16x16x32_bf16 v[26:29], v[142:145], v[190:193], v[26:29]
	v_mfma_f32_16x16x32_bf16 v[14:17], v[130:133], v[194:197], v[14:17]
	v_mfma_f32_16x16x32_bf16 v[14:17], v[134:137], v[204:207], v[14:17]
	v_mfma_f32_16x16x32_bf16 v[10:13], v[138:141], v[194:197], v[10:13]
	v_mfma_f32_16x16x32_bf16 v[10:13], v[142:145], v[204:207], v[10:13]
	v_mfma_f32_16x16x32_bf16 v[54:57], v[146:149], v[162:165], v[54:57]
	v_mfma_f32_16x16x32_bf16 v[54:57], v[150:153], v[166:169], v[54:57]
	v_mfma_f32_16x16x32_bf16 v[50:53], v[154:157], v[162:165], v[50:53]
	v_mfma_f32_16x16x32_bf16 v[50:53], v[158:161], v[166:169], v[50:53]
	v_mfma_f32_16x16x32_bf16 v[38:41], v[146:149], v[170:173], v[38:41]
	v_mfma_f32_16x16x32_bf16 v[38:41], v[150:153], v[174:177], v[38:41]
	v_mfma_f32_16x16x32_bf16 v[34:37], v[154:157], v[170:173], v[34:37]
	v_mfma_f32_16x16x32_bf16 v[34:37], v[158:161], v[174:177], v[34:37]
	v_mfma_f32_16x16x32_bf16 v[22:25], v[146:149], v[186:189], v[22:25]
	v_mfma_f32_16x16x32_bf16 v[22:25], v[150:153], v[190:193], v[22:25]
	v_mfma_f32_16x16x32_bf16 v[18:21], v[154:157], v[186:189], v[18:21]
	v_mfma_f32_16x16x32_bf16 v[18:21], v[158:161], v[190:193], v[18:21]
	v_mfma_f32_16x16x32_bf16 v[6:9], v[146:149], v[194:197], v[6:9]
	v_mfma_f32_16x16x32_bf16 v[6:9], v[150:153], v[204:207], v[6:9]
	v_mfma_f32_16x16x32_bf16 v[2:5], v[154:157], v[194:197], v[2:5]
	v_mfma_f32_16x16x32_bf16 v[2:5], v[158:161], v[204:207], v[2:5]
	s_barrier
	s_add_i32 s55, s55, 2
	s_add_i32 s56, s56, 0x10000
	s_cmpk_gt_u32 s55, 0x7d
	s_mov_b64 s[36:37], s[38:39]
	s_cbranch_scc0 .LBB0_519
	s_and_b64 vcc, exec, s[18:19]
	s_cbranch_vccz .LBB0_522
	s_barrier

.LBB0_612:
	ds_read_b128 v[166:169], v152
	ds_read_b128 v[170:173], v152 offset:1024
	ds_read_b128 v[174:177], v152 offset:2048
	ds_read_b128 v[178:181], v152 offset:3072
	ds_read_b128 v[182:185], v153
	ds_read_b128 v[186:189], v153 offset:1024
	ds_read_b128 v[190:193], v153 offset:2048
	ds_read_b128 v[194:197], v153 offset:3072
	s_add_u32 s26, s4, s22
	s_addc_u32 s27, s5, s23
	s_add_u32 s30, s26, 0x100
	s_addc_u32 s31, s27, 0
	s_add_u32 s28, s52, s22
	s_addc_u32 s29, s53, s23
	s_add_u32 s26, s26, 0x180
	s_addc_u32 s27, s27, 0
	s_cmpk_eq_i32 s22, 0x1f00
	s_cselect_b32 s27, s51, s27
	s_cselect_b32 s26, s50, s26
	s_cselect_b32 s29, s21, s29
	s_cselect_b32 s28, s20, s28
	s_cselect_b32 s31, s19, s31
	s_cselect_b32 s30, s18, s30
	s_mov_b32 m0, s37
	v_lshl_add_u64 v[210:211], v[148:149], 0, s[22:23]
	ds_read_b128 v[198:201], v154
	ds_read_b128 v[202:205], v154 offset:1024
	ds_read_b128 v[206:209], v154 offset:2048
	ds_read_b128 v[214:217], v154 offset:3072
	ds_read_b128 v[218:221], v154 offset:4096
	ds_read_b128 v[222:225], v154 offset:5120
	ds_read_b128 v[226:229], v154 offset:6144
	ds_read_b128 v[230:233], v154 offset:7168
	global_load_lds_dwordx4 v[210:211], off
	v_lshl_add_u64 v[210:211], v[150:151], 0, s[22:23]
	s_mov_b32 m0, s38
	s_nop 0
	global_load_lds_dwordx4 v[210:211], off
	s_waitcnt vmcnt(8)
	s_waitcnt lgkmcnt(0)
	s_barrier
	s_waitcnt lgkmcnt(0)
	v_mfma_f32_16x16x32_bf16 v[126:129], v[166:169], v[198:201], v[126:129]
	v_mfma_f32_16x16x32_bf16 v[126:129], v[170:173], v[202:205], v[126:129]
	v_mfma_f32_16x16x32_bf16 v[122:125], v[174:177], v[198:201], v[122:125]
	v_mfma_f32_16x16x32_bf16 v[122:125], v[178:181], v[202:205], v[122:125]
	v_mfma_f32_16x16x32_bf16 v[110:113], v[166:169], v[206:209], v[110:113]
	v_mfma_f32_16x16x32_bf16 v[110:113], v[170:173], v[214:217], v[110:113]
	v_mfma_f32_16x16x32_bf16 v[106:109], v[174:177], v[206:209], v[106:109]
	v_mfma_f32_16x16x32_bf16 v[106:109], v[178:181], v[214:217], v[106:109]
	v_mfma_f32_16x16x32_bf16 v[94:97], v[166:169], v[218:221], v[94:97]
	v_mfma_f32_16x16x32_bf16 v[94:97], v[170:173], v[222:225], v[94:97]
	v_mfma_f32_16x16x32_bf16 v[90:93], v[174:177], v[218:221], v[90:93]
	v_mfma_f32_16x16x32_bf16 v[90:93], v[178:181], v[222:225], v[90:93]
	v_mfma_f32_16x16x32_bf16 v[78:81], v[166:169], v[226:229], v[78:81]
	v_mfma_f32_16x16x32_bf16 v[78:81], v[170:173], v[230:233], v[78:81]
	v_mfma_f32_16x16x32_bf16 v[74:77], v[174:177], v[226:229], v[74:77]
	v_mfma_f32_16x16x32_bf16 v[74:77], v[178:181], v[230:233], v[74:77]
	v_mfma_f32_16x16x32_bf16 v[118:121], v[182:185], v[198:201], v[118:121]
	v_mfma_f32_16x16x32_bf16 v[118:121], v[186:189], v[202:205], v[118:121]
	v_mfma_f32_16x16x32_bf16 v[114:117], v[190:193], v[198:201], v[114:117]
	v_mfma_f32_16x16x32_bf16 v[114:117], v[194:197], v[202:205], v[114:117]
	v_mfma_f32_16x16x32_bf16 v[102:105], v[182:185], v[206:209], v[102:105]
	v_mfma_f32_16x16x32_bf16 v[102:105], v[186:189], v[214:217], v[102:105]
	v_mfma_f32_16x16x32_bf16 v[98:101], v[190:193], v[206:209], v[98:101]
	v_mfma_f32_16x16x32_bf16 v[98:101], v[194:197], v[214:217], v[98:101]
	v_mfma_f32_16x16x32_bf16 v[86:89], v[182:185], v[218:221], v[86:89]
	v_mfma_f32_16x16x32_bf16 v[86:89], v[186:189], v[222:225], v[86:89]
	v_mfma_f32_16x16x32_bf16 v[82:85], v[190:193], v[218:221], v[82:85]
	v_mfma_f32_16x16x32_bf16 v[82:85], v[194:197], v[222:225], v[82:85]
	v_mfma_f32_16x16x32_bf16 v[70:73], v[182:185], v[226:229], v[70:73]
	v_mfma_f32_16x16x32_bf16 v[70:73], v[186:189], v[230:233], v[70:73]
	v_mfma_f32_16x16x32_bf16 v[66:69], v[190:193], v[226:229], v[66:69]
	v_mfma_f32_16x16x32_bf16 v[66:69], v[194:197], v[230:233], v[66:69]
	s_barrier
	s_mov_b32 m0, s39
	s_add_u32 s56, s28, 0x108000
	ds_read_b128 v[198:201], v154 offset:16384
	ds_read_b128 v[202:205], v154 offset:17408
	ds_read_b128 v[206:209], v154 offset:18432
	ds_read_b128 v[214:217], v154 offset:19456
	ds_read_b128 v[218:221], v154 offset:20480
	ds_read_b128 v[222:225], v154 offset:21504
	ds_read_b128 v[226:229], v154 offset:22528
	ds_read_b128 v[230:233], v154 offset:23552
	global_load_lds_dwordx4 v132, s[28:29]
	s_mov_b32 m0, s40
	s_addc_u32 s57, s29, 0
	global_load_lds_dwordx4 v136, s[28:29]
	s_mov_b32 m0, s41
	s_nop 0
	global_load_lds_dwordx4 v132, s[56:57]
	s_mov_b32 m0, s42
	s_nop 0
	global_load_lds_dwordx4 v136, s[56:57]
	s_mov_b32 m0, s2
	s_nop 0
	global_load_lds_dwordx4 v130, s[30:31]
	s_mov_b32 m0, s3
	s_nop 0
	global_load_lds_dwordx4 v134, s[30:31]
	s_waitcnt vmcnt(8)
	s_waitcnt lgkmcnt(0)
	s_barrier
	s_waitcnt lgkmcnt(0)
	v_mfma_f32_16x16x32_bf16 v[62:65], v[166:169], v[198:201], v[62:65]
	v_mfma_f32_16x16x32_bf16 v[62:65], v[170:173], v[202:205], v[62:65]
	v_mfma_f32_16x16x32_bf16 v[58:61], v[174:177], v[198:201], v[58:61]
	v_mfma_f32_16x16x32_bf16 v[58:61], v[178:181], v[202:205], v[58:61]
	v_mfma_f32_16x16x32_bf16 v[46:49], v[166:169], v[206:209], v[46:49]
	v_mfma_f32_16x16x32_bf16 v[46:49], v[170:173], v[214:217], v[46:49]
	v_mfma_f32_16x16x32_bf16 v[42:45], v[174:177], v[206:209], v[42:45]
	v_mfma_f32_16x16x32_bf16 v[42:45], v[178:181], v[214:217], v[42:45]
	v_mfma_f32_16x16x32_bf16 v[30:33], v[166:169], v[218:221], v[30:33]
	v_mfma_f32_16x16x32_bf16 v[30:33], v[170:173], v[222:225], v[30:33]
	v_mfma_f32_16x16x32_bf16 v[26:29], v[174:177], v[218:221], v[26:29]
	v_mfma_f32_16x16x32_bf16 v[26:29], v[178:181], v[222:225], v[26:29]
	v_mfma_f32_16x16x32_bf16 v[14:17], v[166:169], v[226:229], v[14:17]
	v_mfma_f32_16x16x32_bf16 v[14:17], v[170:173], v[230:233], v[14:17]
	v_mfma_f32_16x16x32_bf16 v[10:13], v[174:177], v[226:229], v[10:13]
	v_mfma_f32_16x16x32_bf16 v[10:13], v[178:181], v[230:233], v[10:13]
	v_mfma_f32_16x16x32_bf16 v[54:57], v[182:185], v[198:201], v[54:57]
	v_mfma_f32_16x16x32_bf16 v[54:57], v[186:189], v[202:205], v[54:57]
	v_mfma_f32_16x16x32_bf16 v[50:53], v[190:193], v[198:201], v[50:53]
	v_mfma_f32_16x16x32_bf16 v[50:53], v[194:197], v[202:205], v[50:53]
	v_mfma_f32_16x16x32_bf16 v[38:41], v[182:185], v[206:209], v[38:41]
	v_mfma_f32_16x16x32_bf16 v[38:41], v[186:189], v[214:217], v[38:41]
	v_mfma_f32_16x16x32_bf16 v[34:37], v[190:193], v[206:209], v[34:37]
	v_mfma_f32_16x16x32_bf16 v[34:37], v[194:197], v[214:217], v[34:37]
	v_mfma_f32_16x16x32_bf16 v[22:25], v[182:185], v[218:221], v[22:25]
	v_mfma_f32_16x16x32_bf16 v[22:25], v[186:189], v[222:225], v[22:25]
	v_mfma_f32_16x16x32_bf16 v[18:21], v[190:193], v[218:221], v[18:21]
	v_mfma_f32_16x16x32_bf16 v[18:21], v[194:197], v[222:225], v[18:21]
	v_mfma_f32_16x16x32_bf16 v[6:9], v[182:185], v[226:229], v[6:9]
	v_mfma_f32_16x16x32_bf16 v[6:9], v[186:189], v[230:233], v[6:9]
	v_mfma_f32_16x16x32_bf16 v[2:5], v[190:193], v[226:229], v[2:5]
	v_mfma_f32_16x16x32_bf16 v[2:5], v[194:197], v[230:233], v[2:5]
	s_barrier
	ds_read_b128 v[166:169], v156
	ds_read_b128 v[170:173], v156 offset:1024
	ds_read_b128 v[174:177], v156 offset:2048
	ds_read_b128 v[178:181], v156 offset:3072
	ds_read_b128 v[182:185], v157
	ds_read_b128 v[186:189], v157 offset:1024
	ds_read_b128 v[190:193], v157 offset:2048
	ds_read_b128 v[194:197], v157 offset:3072
	s_add_u32 s30, s30, 0x108000
	s_addc_u32 s31, s31, 0
	s_mov_b32 m0, s33
	ds_read_b128 v[198:201], v154 offset:32768
	ds_read_b128 v[202:205], v154 offset:33792
	ds_read_b128 v[206:209], v154 offset:34816
	ds_read_b128 v[214:217], v154 offset:35840
	ds_read_b128 v[218:221], v154 offset:36864
	ds_read_b128 v[222:225], v154 offset:37888
	ds_read_b128 v[226:229], v154 offset:38912
	ds_read_b128 v[230:233], v154 offset:39936
	global_load_lds_dwordx4 v130, s[30:31]
	s_mov_b32 m0, s34
	s_nop 0
	global_load_lds_dwordx4 v134, s[30:31]
	s_waitcnt vmcnt(8)
	s_waitcnt lgkmcnt(0)
	s_barrier
	s_waitcnt lgkmcnt(0)
	v_mfma_f32_16x16x32_bf16 v[126:129], v[166:169], v[198:201], v[126:129]
	v_mfma_f32_16x16x32_bf16 v[126:129], v[170:173], v[202:205], v[126:129]
	v_mfma_f32_16x16x32_bf16 v[122:125], v[174:177], v[198:201], v[122:125]
	v_mfma_f32_16x16x32_bf16 v[122:125], v[178:181], v[202:205], v[122:125]
	v_mfma_f32_16x16x32_bf16 v[110:113], v[166:169], v[206:209], v[110:113]
	v_mfma_f32_16x16x32_bf16 v[110:113], v[170:173], v[214:217], v[110:113]
	v_mfma_f32_16x16x32_bf16 v[106:109], v[174:177], v[206:209], v[106:109]
	v_mfma_f32_16x16x32_bf16 v[106:109], v[178:181], v[214:217], v[106:109]
	v_mfma_f32_16x16x32_bf16 v[94:97], v[166:169], v[218:221], v[94:97]
	v_mfma_f32_16x16x32_bf16 v[94:97], v[170:173], v[222:225], v[94:97]
	v_mfma_f32_16x16x32_bf16 v[90:93], v[174:177], v[218:221], v[90:93]
	v_mfma_f32_16x16x32_bf16 v[90:93], v[178:181], v[222:225], v[90:93]
	v_mfma_f32_16x16x32_bf16 v[78:81], v[166:169], v[226:229], v[78:81]
	v_mfma_f32_16x16x32_bf16 v[78:81], v[170:173], v[230:233], v[78:81]
	v_mfma_f32_16x16x32_bf16 v[74:77], v[174:177], v[226:229], v[74:77]
	v_mfma_f32_16x16x32_bf16 v[74:77], v[178:181], v[230:233], v[74:77]
	v_mfma_f32_16x16x32_bf16 v[118:121], v[182:185], v[198:201], v[118:121]
	v_mfma_f32_16x16x32_bf16 v[118:121], v[186:189], v[202:205], v[118:121]
	v_mfma_f32_16x16x32_bf16 v[114:117], v[190:193], v[198:201], v[114:117]
	v_mfma_f32_16x16x32_bf16 v[114:117], v[194:197], v[202:205], v[114:117]
	v_mfma_f32_16x16x32_bf16 v[102:105], v[182:185], v[206:209], v[102:105]
	v_mfma_f32_16x16x32_bf16 v[102:105], v[186:189], v[214:217], v[102:105]
	v_mfma_f32_16x16x32_bf16 v[98:101], v[190:193], v[206:209], v[98:101]
	v_mfma_f32_16x16x32_bf16 v[98:101], v[194:197], v[214:217], v[98:101]
	v_mfma_f32_16x16x32_bf16 v[86:89], v[182:185], v[218:221], v[86:89]
	v_mfma_f32_16x16x32_bf16 v[86:89], v[186:189], v[222:225], v[86:89]
	v_mfma_f32_16x16x32_bf16 v[82:85], v[190:193], v[218:221], v[82:85]
	v_mfma_f32_16x16x32_bf16 v[82:85], v[194:197], v[222:225], v[82:85]
	v_mfma_f32_16x16x32_bf16 v[70:73], v[182:185], v[226:229], v[70:73]
	v_mfma_f32_16x16x32_bf16 v[70:73], v[186:189], v[230:233], v[70:73]
	v_mfma_f32_16x16x32_bf16 v[66:69], v[190:193], v[226:229], v[66:69]
	v_mfma_f32_16x16x32_bf16 v[66:69], v[194:197], v[230:233], v[66:69]
	s_barrier
	s_mov_b32 m0, s43
	s_add_u32 s28, s28, 0x80
	s_addc_u32 s29, s29, 0
	ds_read_b128 v[198:201], v154 offset:49152
	ds_read_b128 v[202:205], v154 offset:50176
	ds_read_b128 v[206:209], v154 offset:51200
	ds_read_b128 v[214:217], v154 offset:52224
	ds_read_b128 v[218:221], v154 offset:53248
	ds_read_b128 v[222:225], v154 offset:54272
	ds_read_b128 v[226:229], v154 offset:55296
	ds_read_b128 v[230:233], v154 offset:56320
	global_load_lds_dwordx4 v132, s[28:29]
	s_mov_b32 m0, s44
	s_nop 0
	global_load_lds_dwordx4 v136, s[28:29]
	s_add_u32 s28, s28, 0x108000
	s_addc_u32 s29, s29, 0
	s_mov_b32 m0, s45
	s_nop 0
	global_load_lds_dwordx4 v132, s[28:29]
	s_mov_b32 m0, s46
	s_nop 0
	global_load_lds_dwordx4 v136, s[28:29]
	s_mov_b32 m0, s35
	s_nop 0
	global_load_lds_dwordx4 v130, s[26:27]
	s_mov_b32 m0, s36
	s_nop 0
	global_load_lds_dwordx4 v134, s[26:27]
	s_waitcnt vmcnt(8)
	s_waitcnt lgkmcnt(0)
	s_barrier
	s_waitcnt lgkmcnt(0)
	v_mfma_f32_16x16x32_bf16 v[62:65], v[166:169], v[198:201], v[62:65]
	v_mfma_f32_16x16x32_bf16 v[62:65], v[170:173], v[202:205], v[62:65]
	v_mfma_f32_16x16x32_bf16 v[58:61], v[174:177], v[198:201], v[58:61]
	v_mfma_f32_16x16x32_bf16 v[58:61], v[178:181], v[202:205], v[58:61]
	v_mfma_f32_16x16x32_bf16 v[46:49], v[166:169], v[206:209], v[46:49]
	v_mfma_f32_16x16x32_bf16 v[46:49], v[170:173], v[214:217], v[46:49]
	v_mfma_f32_16x16x32_bf16 v[42:45], v[174:177], v[206:209], v[42:45]
	v_mfma_f32_16x16x32_bf16 v[42:45], v[178:181], v[214:217], v[42:45]
	v_mfma_f32_16x16x32_bf16 v[30:33], v[166:169], v[218:221], v[30:33]
	v_mfma_f32_16x16x32_bf16 v[30:33], v[170:173], v[222:225], v[30:33]
	v_mfma_f32_16x16x32_bf16 v[26:29], v[174:177], v[218:221], v[26:29]
	v_mfma_f32_16x16x32_bf16 v[26:29], v[178:181], v[222:225], v[26:29]
	v_mfma_f32_16x16x32_bf16 v[14:17], v[166:169], v[226:229], v[14:17]
	v_mfma_f32_16x16x32_bf16 v[14:17], v[170:173], v[230:233], v[14:17]
	v_mfma_f32_16x16x32_bf16 v[10:13], v[174:177], v[226:229], v[10:13]
	v_mfma_f32_16x16x32_bf16 v[10:13], v[178:181], v[230:233], v[10:13]
	v_mfma_f32_16x16x32_bf16 v[54:57], v[182:185], v[198:201], v[54:57]
	v_mfma_f32_16x16x32_bf16 v[54:57], v[186:189], v[202:205], v[54:57]
	v_mfma_f32_16x16x32_bf16 v[50:53], v[190:193], v[198:201], v[50:53]
	v_mfma_f32_16x16x32_bf16 v[50:53], v[194:197], v[202:205], v[50:53]
	v_mfma_f32_16x16x32_bf16 v[38:41], v[182:185], v[206:209], v[38:41]
	v_mfma_f32_16x16x32_bf16 v[38:41], v[186:189], v[214:217], v[38:41]
	v_mfma_f32_16x16x32_bf16 v[34:37], v[190:193], v[206:209], v[34:37]
	v_mfma_f32_16x16x32_bf16 v[34:37], v[194:197], v[214:217], v[34:37]
	v_mfma_f32_16x16x32_bf16 v[22:25], v[182:185], v[218:221], v[22:25]
	v_mfma_f32_16x16x32_bf16 v[22:25], v[186:189], v[222:225], v[22:25]
	v_mfma_f32_16x16x32_bf16 v[18:21], v[190:193], v[218:221], v[18:21]
	v_mfma_f32_16x16x32_bf16 v[18:21], v[194:197], v[222:225], v[18:21]
	v_mfma_f32_16x16x32_bf16 v[6:9], v[182:185], v[226:229], v[6:9]
	v_mfma_f32_16x16x32_bf16 v[6:9], v[186:189], v[230:233], v[6:9]
	v_mfma_f32_16x16x32_bf16 v[2:5], v[190:193], v[226:229], v[2:5]
	v_mfma_f32_16x16x32_bf16 v[2:5], v[194:197], v[230:233], v[2:5]
	s_barrier
	s_add_i32 s54, s54, 2
	s_add_u32 s22, s22, 0x100
	s_addc_u32 s23, s23, 0
	s_cmp_gt_u32 s54, 61
	s_cbranch_scc0 .LBB0_612
	s_and_b64 vcc, exec, s[16:17]
	s_cbranch_vccz .LBB0_615
	s_barrier

.LBB0_844:
	s_add_i32 s35, s52, 0xfffe8000
	s_and_b32 s34, s30, 0x100
	s_and_b32 s35, s35, 0x3e0000
	s_or_b32 s34, s34, s35
	s_add_u32 s53, s28, s34
	s_addc_u32 s55, s29, 0
	s_add_u32 s34, s30, 0x100
	s_addc_u32 s35, s31, 0
	s_add_i32 s37, s52, 0xffff8000
	s_and_b32 s36, s34, 0x100
	s_and_b32 s37, s37, 0x7e0000
	s_or_b32 s36, s37, s36
	s_add_u32 s36, s28, s36
	s_addc_u32 s37, s29, 0
	s_add_u32 s54, s49, s30
	s_addc_u32 s31, s50, s31
	s_add_i32 s38, s30, 0x180
	s_and_b32 s38, s38, 0x180
	s_and_b32 s39, s52, 0x7e0000
	s_or_b32 s38, s39, s38
	s_add_u32 s56, s28, s38
	s_addc_u32 s57, s29, 0
	s_cmpk_eq_i32 s30, 0x3f00
	s_cselect_b32 s39, s1, s37
	s_cselect_b32 s38, s21, s36
	s_cselect_b32 s37, s23, s31
	s_cselect_b32 s36, s22, s54
	s_cselect_b32 s31, s48, s57
	s_cselect_b32 s30, s27, s56
	s_add_i32 s56, 0, 0x10000
	v_add_u32_e32 v124, s56, v211
	ds_read_b128 v[104:107], v124
	ds_read_b128 v[108:111], v124 offset:1024
	ds_read_b128 v[120:123], v124 offset:2048
	ds_read_b128 v[124:127], v124 offset:3072
	ds_read_b128 v[144:147], v214
	ds_read_b128 v[148:151], v214 offset:1024
	ds_read_b128 v[152:155], v214 offset:2048
	ds_read_b128 v[156:159], v214 offset:3072
	s_add_u32 s54, s53, 0x10080
	s_addc_u32 s55, s55, 0
	s_add_i32 m0, s3, 0xc000
	ds_read_b128 v[160:163], v215
	ds_read_b128 v[164:167], v215 offset:1024
	ds_read_b128 v[168:171], v215 offset:2048
	ds_read_b128 v[172:175], v215 offset:3072
	ds_read_b128 v[176:179], v215 offset:4096
	ds_read_b128 v[180:183], v215 offset:5120
	ds_read_b128 v[192:195], v215 offset:6144
	ds_read_b128 v[196:199], v215 offset:7168
	global_load_lds_dwordx4 v184, s[54:55]
	s_add_i32 m0, s3, 0xe000
	s_nop 0
	global_load_lds_dwordx4 v188, s[54:55]
	s_waitcnt vmcnt(8)
	s_waitcnt lgkmcnt(0)
	s_barrier
	s_waitcnt lgkmcnt(0)
	v_mfma_f32_16x16x32_bf16 v[140:143], v[104:107], v[160:163], v[140:143]
	v_mfma_f32_16x16x32_bf16 v[140:143], v[108:111], v[164:167], v[140:143]
	v_mfma_f32_16x16x32_bf16 v[136:139], v[120:123], v[160:163], v[136:139]
	v_mfma_f32_16x16x32_bf16 v[136:139], v[124:127], v[164:167], v[136:139]
	v_mfma_f32_16x16x32_bf16 v[116:119], v[104:107], v[168:171], v[116:119]
	v_mfma_f32_16x16x32_bf16 v[116:119], v[108:111], v[172:175], v[116:119]
	v_mfma_f32_16x16x32_bf16 v[112:115], v[120:123], v[168:171], v[112:115]
	v_mfma_f32_16x16x32_bf16 v[112:115], v[124:127], v[172:175], v[112:115]
	v_mfma_f32_16x16x32_bf16 v[92:95], v[104:107], v[176:179], v[92:95]
	v_mfma_f32_16x16x32_bf16 v[92:95], v[108:111], v[180:183], v[92:95]
	v_mfma_f32_16x16x32_bf16 v[88:91], v[120:123], v[176:179], v[88:91]
	v_mfma_f32_16x16x32_bf16 v[88:91], v[124:127], v[180:183], v[88:91]
	v_mfma_f32_16x16x32_bf16 v[76:79], v[104:107], v[192:195], v[76:79]
	v_mfma_f32_16x16x32_bf16 v[76:79], v[108:111], v[196:199], v[76:79]
	v_mfma_f32_16x16x32_bf16 v[72:75], v[120:123], v[192:195], v[72:75]
	v_mfma_f32_16x16x32_bf16 v[72:75], v[124:127], v[196:199], v[72:75]
	v_mfma_f32_16x16x32_bf16 v[132:135], v[144:147], v[160:163], v[132:135]
	v_mfma_f32_16x16x32_bf16 v[132:135], v[148:151], v[164:167], v[132:135]
	v_mfma_f32_16x16x32_bf16 v[128:131], v[152:155], v[160:163], v[128:131]
	v_mfma_f32_16x16x32_bf16 v[128:131], v[156:159], v[164:167], v[128:131]
	v_mfma_f32_16x16x32_bf16 v[100:103], v[144:147], v[168:171], v[100:103]
	v_mfma_f32_16x16x32_bf16 v[100:103], v[148:151], v[172:175], v[100:103]
	v_mfma_f32_16x16x32_bf16 v[96:99], v[152:155], v[168:171], v[96:99]
	v_mfma_f32_16x16x32_bf16 v[96:99], v[156:159], v[172:175], v[96:99]
	v_mfma_f32_16x16x32_bf16 v[84:87], v[144:147], v[176:179], v[84:87]
	v_mfma_f32_16x16x32_bf16 v[84:87], v[148:151], v[180:183], v[84:87]
	v_mfma_f32_16x16x32_bf16 v[80:83], v[152:155], v[176:179], v[80:83]
	v_mfma_f32_16x16x32_bf16 v[80:83], v[156:159], v[180:183], v[80:83]
	v_mfma_f32_16x16x32_bf16 v[68:71], v[144:147], v[192:195], v[68:71]
	v_mfma_f32_16x16x32_bf16 v[68:71], v[148:151], v[196:199], v[68:71]
	v_mfma_f32_16x16x32_bf16 v[64:67], v[152:155], v[192:195], v[64:67]
	v_mfma_f32_16x16x32_bf16 v[64:67], v[156:159], v[196:199], v[64:67]
	s_barrier
	s_add_i32 s53, s56, s2
	v_lshl_add_u64 v[200:201], s[36:37], 0, v[186:187]
	s_mov_b32 m0, s53
	ds_read_b128 v[160:163], v215 offset:16384
	ds_read_b128 v[164:167], v215 offset:17408
	ds_read_b128 v[168:171], v215 offset:18432
	ds_read_b128 v[172:175], v215 offset:19456
	ds_read_b128 v[176:179], v215 offset:20480
	ds_read_b128 v[180:183], v215 offset:21504
	ds_read_b128 v[192:195], v215 offset:22528
	ds_read_b128 v[196:199], v215 offset:23552
	global_load_lds_dwordx4 v[200:201], off
	s_add_i32 m0, s53, 0x2000
	s_add_u32 s54, s36, 0x208000
	v_lshl_add_u64 v[202:203], s[36:37], 0, v[190:191]
	s_addc_u32 s55, s37, 0
	s_add_i32 s53, s45, s2
	global_load_lds_dwordx4 v[202:203], off
	s_mov_b32 m0, s53
	s_nop 0
	global_load_lds_dwordx4 v186, s[54:55]
	s_add_i32 m0, s53, 0x2000
	s_nop 0
	global_load_lds_dwordx4 v190, s[54:55]
	s_mov_b32 m0, s3
	s_nop 0
	global_load_lds_dwordx4 v184, s[38:39]
	s_mov_b32 m0, s33
	s_nop 0
	global_load_lds_dwordx4 v188, s[38:39]
	s_waitcnt vmcnt(8)
	s_waitcnt lgkmcnt(0)
	s_barrier
	s_waitcnt lgkmcnt(0)
	v_mfma_f32_16x16x32_bf16 v[60:63], v[104:107], v[160:163], v[60:63]
	v_mfma_f32_16x16x32_bf16 v[60:63], v[108:111], v[164:167], v[60:63]
	v_mfma_f32_16x16x32_bf16 v[56:59], v[120:123], v[160:163], v[56:59]
	v_mfma_f32_16x16x32_bf16 v[56:59], v[124:127], v[164:167], v[56:59]
	v_mfma_f32_16x16x32_bf16 v[44:47], v[104:107], v[168:171], v[44:47]
	v_mfma_f32_16x16x32_bf16 v[44:47], v[108:111], v[172:175], v[44:47]
	v_mfma_f32_16x16x32_bf16 v[40:43], v[120:123], v[168:171], v[40:43]
	v_mfma_f32_16x16x32_bf16 v[40:43], v[124:127], v[172:175], v[40:43]
	v_mfma_f32_16x16x32_bf16 v[28:31], v[104:107], v[176:179], v[28:31]
	v_mfma_f32_16x16x32_bf16 v[28:31], v[108:111], v[180:183], v[28:31]
	v_mfma_f32_16x16x32_bf16 v[24:27], v[120:123], v[176:179], v[24:27]
	v_mfma_f32_16x16x32_bf16 v[24:27], v[124:127], v[180:183], v[24:27]
	v_mfma_f32_16x16x32_bf16 v[12:15], v[104:107], v[192:195], v[12:15]
	v_mfma_f32_16x16x32_bf16 v[12:15], v[108:111], v[196:199], v[12:15]
	v_mfma_f32_16x16x32_bf16 v[8:11], v[120:123], v[192:195], v[8:11]
	v_mfma_f32_16x16x32_bf16 v[8:11], v[124:127], v[196:199], v[8:11]
	v_mfma_f32_16x16x32_bf16 v[52:55], v[144:147], v[160:163], v[52:55]
	v_mfma_f32_16x16x32_bf16 v[52:55], v[148:151], v[164:167], v[52:55]
	v_mfma_f32_16x16x32_bf16 v[48:51], v[152:155], v[160:163], v[48:51]
	v_mfma_f32_16x16x32_bf16 v[48:51], v[156:159], v[164:167], v[48:51]
	v_mfma_f32_16x16x32_bf16 v[36:39], v[144:147], v[168:171], v[36:39]
	v_mfma_f32_16x16x32_bf16 v[36:39], v[148:151], v[172:175], v[36:39]
	v_mfma_f32_16x16x32_bf16 v[32:35], v[152:155], v[168:171], v[32:35]
	v_mfma_f32_16x16x32_bf16 v[32:35], v[156:159], v[172:175], v[32:35]
	v_mfma_f32_16x16x32_bf16 v[20:23], v[144:147], v[176:179], v[20:23]
	v_mfma_f32_16x16x32_bf16 v[20:23], v[148:151], v[180:183], v[20:23]
	v_mfma_f32_16x16x32_bf16 v[16:19], v[152:155], v[176:179], v[16:19]
	v_mfma_f32_16x16x32_bf16 v[16:19], v[156:159], v[180:183], v[16:19]
	v_mfma_f32_16x16x32_bf16 v[4:7], v[144:147], v[192:195], v[4:7]
	v_mfma_f32_16x16x32_bf16 v[4:7], v[148:151], v[196:199], v[4:7]
	v_mfma_f32_16x16x32_bf16 v[0:3], v[152:155], v[192:195], v[0:3]
	v_mfma_f32_16x16x32_bf16 v[0:3], v[156:159], v[196:199], v[0:3]
	s_barrier
	s_add_i32 s53, 0, 0x18000
	s_add_i32 s54, 0, 0x1c000
	v_add_u32_e32 v124, s53, v211
	v_add_u32_e32 v156, s54, v211
	ds_read_b128 v[104:107], v124
	ds_read_b128 v[108:111], v124 offset:1024
	ds_read_b128 v[120:123], v124 offset:2048
	ds_read_b128 v[124:127], v124 offset:3072
	ds_read_b128 v[144:147], v156
	ds_read_b128 v[148:151], v156 offset:1024
	ds_read_b128 v[152:155], v156 offset:2048
	ds_read_b128 v[156:159], v156 offset:3072
	s_add_u32 s38, s38, 0x10000
	s_addc_u32 s39, s39, 0
	s_mov_b32 m0, s40
	ds_read_b128 v[160:163], v215 offset:32768
	ds_read_b128 v[164:167], v215 offset:33792
	ds_read_b128 v[168:171], v215 offset:34816
	ds_read_b128 v[172:175], v215 offset:35840
	ds_read_b128 v[176:179], v215 offset:36864
	ds_read_b128 v[180:183], v215 offset:37888
	ds_read_b128 v[192:195], v215 offset:38912
	ds_read_b128 v[196:199], v215 offset:39936
	global_load_lds_dwordx4 v184, s[38:39]
	v_lshl_add_u64 v[204:205], s[38:39], 0, v[188:189]
	s_mov_b32 m0, s41
	s_nop 0
	global_load_lds_dwordx4 v[204:205], off
	s_waitcnt vmcnt(8)
	s_waitcnt lgkmcnt(0)
	s_barrier
	s_waitcnt lgkmcnt(0)
	v_mfma_f32_16x16x32_bf16 v[140:143], v[104:107], v[160:163], v[140:143]
	v_mfma_f32_16x16x32_bf16 v[140:143], v[108:111], v[164:167], v[140:143]
	v_mfma_f32_16x16x32_bf16 v[136:139], v[120:123], v[160:163], v[136:139]
	v_mfma_f32_16x16x32_bf16 v[136:139], v[124:127], v[164:167], v[136:139]
	v_mfma_f32_16x16x32_bf16 v[116:119], v[104:107], v[168:171], v[116:119]
	v_mfma_f32_16x16x32_bf16 v[116:119], v[108:111], v[172:175], v[116:119]
	v_mfma_f32_16x16x32_bf16 v[112:115], v[120:123], v[168:171], v[112:115]
	v_mfma_f32_16x16x32_bf16 v[112:115], v[124:127], v[172:175], v[112:115]
	v_mfma_f32_16x16x32_bf16 v[92:95], v[104:107], v[176:179], v[92:95]
	v_mfma_f32_16x16x32_bf16 v[92:95], v[108:111], v[180:183], v[92:95]
	v_mfma_f32_16x16x32_bf16 v[88:91], v[120:123], v[176:179], v[88:91]
	v_mfma_f32_16x16x32_bf16 v[88:91], v[124:127], v[180:183], v[88:91]
	v_mfma_f32_16x16x32_bf16 v[76:79], v[104:107], v[192:195], v[76:79]
	v_mfma_f32_16x16x32_bf16 v[76:79], v[108:111], v[196:199], v[76:79]
	v_mfma_f32_16x16x32_bf16 v[72:75], v[120:123], v[192:195], v[72:75]
	v_mfma_f32_16x16x32_bf16 v[72:75], v[124:127], v[196:199], v[72:75]
	v_mfma_f32_16x16x32_bf16 v[132:135], v[144:147], v[160:163], v[132:135]
	v_mfma_f32_16x16x32_bf16 v[132:135], v[148:151], v[164:167], v[132:135]
	v_mfma_f32_16x16x32_bf16 v[128:131], v[152:155], v[160:163], v[128:131]
	v_mfma_f32_16x16x32_bf16 v[128:131], v[156:159], v[164:167], v[128:131]
	v_mfma_f32_16x16x32_bf16 v[100:103], v[144:147], v[168:171], v[100:103]
	v_mfma_f32_16x16x32_bf16 v[100:103], v[148:151], v[172:175], v[100:103]
	v_mfma_f32_16x16x32_bf16 v[96:99], v[152:155], v[168:171], v[96:99]
	v_mfma_f32_16x16x32_bf16 v[96:99], v[156:159], v[172:175], v[96:99]
	v_mfma_f32_16x16x32_bf16 v[84:87], v[144:147], v[176:179], v[84:87]
	v_mfma_f32_16x16x32_bf16 v[84:87], v[148:151], v[180:183], v[84:87]
	v_mfma_f32_16x16x32_bf16 v[80:83], v[152:155], v[176:179], v[80:83]
	v_mfma_f32_16x16x32_bf16 v[80:83], v[156:159], v[180:183], v[80:83]
	v_mfma_f32_16x16x32_bf16 v[68:71], v[144:147], v[192:195], v[68:71]
	v_mfma_f32_16x16x32_bf16 v[68:71], v[148:151], v[196:199], v[68:71]
	v_mfma_f32_16x16x32_bf16 v[64:67], v[152:155], v[192:195], v[64:67]
	v_mfma_f32_16x16x32_bf16 v[64:67], v[156:159], v[196:199], v[64:67]
	s_barrier
	s_add_i32 s38, s53, s2
	v_lshl_add_u64 v[200:201], v[200:201], 0, s[16:17]
	s_mov_b32 m0, s38
	ds_read_b128 v[160:163], v215 offset:49152
	ds_read_b128 v[164:167], v215 offset:50176
	ds_read_b128 v[168:171], v215 offset:51200
	ds_read_b128 v[172:175], v215 offset:52224
	ds_read_b128 v[176:179], v215 offset:53248
	ds_read_b128 v[180:183], v215 offset:54272
	ds_read_b128 v[192:195], v215 offset:55296
	ds_read_b128 v[196:199], v215 offset:56320
	global_load_lds_dwordx4 v[200:201], off
	s_add_i32 m0, s38, 0x2000
	s_add_u32 s36, s36, 0x208080
	v_lshl_add_u64 v[200:201], v[202:203], 0, s[16:17]
	s_addc_u32 s37, s37, 0
	s_add_i32 s38, s54, s2
	global_load_lds_dwordx4 v[200:201], off
	s_mov_b32 m0, s38
	s_nop 0
	global_load_lds_dwordx4 v186, s[36:37]
	s_add_i32 m0, s38, 0x2000
	s_nop 0
	global_load_lds_dwordx4 v190, s[36:37]
	s_mov_b32 m0, s43
	s_nop 0
	global_load_lds_dwordx4 v184, s[30:31]
	v_lshl_add_u64 v[200:201], s[30:31], 0, v[188:189]
	s_mov_b32 m0, s44
	s_nop 0
	global_load_lds_dwordx4 v[200:201], off
	s_waitcnt vmcnt(8)
	s_waitcnt lgkmcnt(0)
	s_barrier
	s_waitcnt lgkmcnt(0)
	v_mfma_f32_16x16x32_bf16 v[60:63], v[104:107], v[160:163], v[60:63]
	v_mfma_f32_16x16x32_bf16 v[60:63], v[108:111], v[164:167], v[60:63]
	v_mfma_f32_16x16x32_bf16 v[56:59], v[120:123], v[160:163], v[56:59]
	v_mfma_f32_16x16x32_bf16 v[56:59], v[124:127], v[164:167], v[56:59]
	v_mfma_f32_16x16x32_bf16 v[44:47], v[104:107], v[168:171], v[44:47]
	v_mfma_f32_16x16x32_bf16 v[44:47], v[108:111], v[172:175], v[44:47]
	v_mfma_f32_16x16x32_bf16 v[40:43], v[120:123], v[168:171], v[40:43]
	v_mfma_f32_16x16x32_bf16 v[40:43], v[124:127], v[172:175], v[40:43]
	v_mfma_f32_16x16x32_bf16 v[28:31], v[104:107], v[176:179], v[28:31]
	v_mfma_f32_16x16x32_bf16 v[28:31], v[108:111], v[180:183], v[28:31]
	v_mfma_f32_16x16x32_bf16 v[24:27], v[120:123], v[176:179], v[24:27]
	v_mfma_f32_16x16x32_bf16 v[24:27], v[124:127], v[180:183], v[24:27]
	v_mfma_f32_16x16x32_bf16 v[12:15], v[104:107], v[192:195], v[12:15]
	v_mfma_f32_16x16x32_bf16 v[12:15], v[108:111], v[196:199], v[12:15]
	v_mfma_f32_16x16x32_bf16 v[8:11], v[120:123], v[192:195], v[8:11]
	v_mfma_f32_16x16x32_bf16 v[8:11], v[124:127], v[196:199], v[8:11]
	v_mfma_f32_16x16x32_bf16 v[52:55], v[144:147], v[160:163], v[52:55]
	v_mfma_f32_16x16x32_bf16 v[52:55], v[148:151], v[164:167], v[52:55]
	v_mfma_f32_16x16x32_bf16 v[48:51], v[152:155], v[160:163], v[48:51]
	v_mfma_f32_16x16x32_bf16 v[48:51], v[156:159], v[164:167], v[48:51]
	v_mfma_f32_16x16x32_bf16 v[36:39], v[144:147], v[168:171], v[36:39]
	v_mfma_f32_16x16x32_bf16 v[36:39], v[148:151], v[172:175], v[36:39]
	v_mfma_f32_16x16x32_bf16 v[32:35], v[152:155], v[168:171], v[32:35]
	v_mfma_f32_16x16x32_bf16 v[32:35], v[156:159], v[172:175], v[32:35]
	v_mfma_f32_16x16x32_bf16 v[20:23], v[144:147], v[176:179], v[20:23]
	v_mfma_f32_16x16x32_bf16 v[20:23], v[148:151], v[180:183], v[20:23]
	v_mfma_f32_16x16x32_bf16 v[16:19], v[152:155], v[176:179], v[16:19]
	v_mfma_f32_16x16x32_bf16 v[16:19], v[156:159], v[180:183], v[16:19]
	v_mfma_f32_16x16x32_bf16 v[4:7], v[144:147], v[192:195], v[4:7]
	v_mfma_f32_16x16x32_bf16 v[4:7], v[148:151], v[196:199], v[4:7]
	v_mfma_f32_16x16x32_bf16 v[0:3], v[152:155], v[192:195], v[0:3]
	v_mfma_f32_16x16x32_bf16 v[0:3], v[156:159], v[196:199], v[0:3]
	s_barrier
	s_add_i32 s51, s51, 2
	s_add_i32 s52, s52, 0x10000
	s_cmpk_gt_u32 s51, 0x7d
	s_mov_b64 s[30:31], s[34:35]
	s_cbranch_scc0 .LBB0_844
	s_and_b64 vcc, exec, s[18:19]
	s_cbranch_vccz .LBB0_847
	s_barrier
